# LRU GEMM epilogue: n=0 half-results parked in dead accumulator registers and stored with the n=1 half as one 16-byte store per lane (16 dwordx4 instead of 32 dwordx2 stores with holes)
# speedup vs baseline: 1.0222x; 1.0052x over previous
.LBB0_1205:
	s_ashr_i32 s21, s20, 31
	s_lshl_b64 s[26:27], s[20:21], 17
	s_add_u32 s26, s36, s26
	s_addc_u32 s27, s37, s27
	s_and_b64 s[6:7], s[6:7], exec
	s_cselect_b32 s7, s27, s31
	s_cselect_b32 s6, s26, s30
	s_add_i32 s23, 0, 0x10000
	v_add_u32_e32 v173, s23, v1
	ds_read_b128 v[2:5], v173
	ds_read_b128 v[6:9], v173 offset:1024
	ds_read_b128 v[10:13], v173 offset:2048
	ds_read_b128 v[14:17], v173 offset:3072
	s_add_u32 s46, s28, 0x40080
	s_addc_u32 s47, s29, 0
	s_add_i32 s50, s3, 0xc000
	v_lshl_add_u64 v[50:51], s[46:47], 0, v[138:139]
	s_mov_b32 m0, s50
	s_add_i32 s21, s3, 0xe000
	ds_read_b128 v[18:21], v172
	ds_read_b128 v[22:25], v172 offset:1024
	ds_read_b128 v[26:29], v172 offset:2048
	ds_read_b128 v[30:33], v172 offset:3072
	ds_read_b128 v[34:37], v172 offset:4096
	ds_read_b128 v[38:41], v172 offset:5120
	ds_read_b128 v[42:45], v172 offset:6144
	ds_read_b128 v[46:49], v172 offset:7168
	global_load_lds_dwordx4 v[50:51], off
	v_lshl_add_u64 v[50:51], s[46:47], 0, v[142:143]
	s_mov_b32 m0, s21
	s_nop 0
	global_load_lds_dwordx4 v[50:51], off
	s_waitcnt lgkmcnt(8)
	s_barrier
	s_waitcnt lgkmcnt(0)
	s_waitcnt lgkmcnt(0)
	v_mfma_f32_16x16x32_bf16 v[50:53], v[2:5], v[18:21], 0
	v_mfma_f32_16x16x32_bf16 v[54:57], v[10:13], v[18:21], 0
	v_mfma_f32_16x16x32_bf16 v[58:61], v[2:5], v[26:29], 0
	v_mfma_f32_16x16x32_bf16 v[62:65], v[10:13], v[26:29], 0
	v_mfma_f32_16x16x32_bf16 v[66:69], v[2:5], v[34:37], 0
	v_mfma_f32_16x16x32_bf16 v[70:73], v[10:13], v[34:37], 0
	v_mfma_f32_16x16x32_bf16 v[74:77], v[2:5], v[42:45], 0
	v_mfma_f32_16x16x32_bf16 v[78:81], v[10:13], v[42:45], 0
	v_mfma_f32_16x16x32_bf16 v[50:53], v[6:9], v[22:25], v[50:53]
	v_mfma_f32_16x16x32_bf16 v[54:57], v[14:17], v[22:25], v[54:57]
	v_mfma_f32_16x16x32_bf16 v[58:61], v[6:9], v[30:33], v[58:61]
	v_mfma_f32_16x16x32_bf16 v[62:65], v[14:17], v[30:33], v[62:65]
	v_mfma_f32_16x16x32_bf16 v[66:69], v[6:9], v[38:41], v[66:69]
	v_mfma_f32_16x16x32_bf16 v[70:73], v[14:17], v[38:41], v[70:73]
	v_mfma_f32_16x16x32_bf16 v[74:77], v[6:9], v[46:49], v[74:77]
	v_mfma_f32_16x16x32_bf16 v[78:81], v[14:17], v[46:49], v[78:81]
	s_barrier
	s_add_i32 s48, 0, 0x14000
	v_lshl_add_u64 v[170:171], s[30:31], 0, v[140:141]
	s_mov_b64 s[52:53], 0x100
	s_add_i32 s47, s23, s38
	v_add_u32_e32 v220, s48, v1
	v_lshl_add_u64 v[98:99], v[170:171], 0, s[52:53]
	s_mov_b32 m0, s47
	v_lshl_add_u64 v[186:187], s[30:31], 0, v[144:145]
	s_add_i32 s23, s47, 0x2000
	ds_read_b128 v[82:85], v220
	ds_read_b128 v[86:89], v220 offset:1024
	ds_read_b128 v[90:93], v220 offset:2048
	ds_read_b128 v[94:97], v220 offset:3072
	global_load_lds_dwordx4 v[98:99], off
	v_lshl_add_u64 v[98:99], v[186:187], 0, s[52:53]
	s_mov_b32 m0, s23
	s_nop 0
	global_load_lds_dwordx4 v[98:99], off
	s_barrier
	s_waitcnt lgkmcnt(0)
	s_waitcnt lgkmcnt(0)
	v_mfma_f32_16x16x32_bf16 v[98:101], v[82:85], v[18:21], 0
	v_mfma_f32_16x16x32_bf16 v[18:21], v[90:93], v[18:21], 0
	v_mfma_f32_16x16x32_bf16 v[98:101], v[86:89], v[22:25], v[98:101]
	v_mfma_f32_16x16x32_bf16 v[18:21], v[94:97], v[22:25], v[18:21]
	v_mfma_f32_16x16x32_bf16 v[22:25], v[82:85], v[26:29], 0
	v_mfma_f32_16x16x32_bf16 v[26:29], v[90:93], v[26:29], 0
	v_mfma_f32_16x16x32_bf16 v[22:25], v[86:89], v[30:33], v[22:25]
	v_mfma_f32_16x16x32_bf16 v[26:29], v[94:97], v[30:33], v[26:29]
	v_mfma_f32_16x16x32_bf16 v[30:33], v[82:85], v[34:37], 0
	v_mfma_f32_16x16x32_bf16 v[34:37], v[90:93], v[34:37], 0
	v_mfma_f32_16x16x32_bf16 v[30:33], v[86:89], v[38:41], v[30:33]
	v_mfma_f32_16x16x32_bf16 v[34:37], v[94:97], v[38:41], v[34:37]
	v_mfma_f32_16x16x32_bf16 v[38:41], v[82:85], v[42:45], 0
	v_mfma_f32_16x16x32_bf16 v[42:45], v[90:93], v[42:45], 0
	v_mfma_f32_16x16x32_bf16 v[38:41], v[86:89], v[46:49], v[38:41]
	v_mfma_f32_16x16x32_bf16 v[42:45], v[94:97], v[46:49], v[42:45]
	v_lshl_add_u64 v[188:189], s[28:29], 0, v[138:139]
	s_mov_b32 m0, s3
	v_lshl_add_u64 v[130:131], v[188:189], 0, s[52:53]
	v_lshl_add_u64 v[218:219], s[28:29], 0, v[142:143]
	s_barrier
	ds_read_b128 v[46:49], v172 offset:16384
	ds_read_b128 v[102:105], v172 offset:17408
	ds_read_b128 v[106:109], v172 offset:18432
	ds_read_b128 v[110:113], v172 offset:19456
	ds_read_b128 v[114:117], v172 offset:20480
	ds_read_b128 v[118:121], v172 offset:21504
	ds_read_b128 v[122:125], v172 offset:22528
	ds_read_b128 v[126:129], v172 offset:23552
	global_load_lds_dwordx4 v[130:131], off
	v_lshl_add_u64 v[130:131], v[218:219], 0, s[52:53]
	s_mov_b32 m0, s39
	s_nop 0
	global_load_lds_dwordx4 v[130:131], off
	s_barrier
	s_waitcnt lgkmcnt(0)
	s_waitcnt lgkmcnt(0)
	v_mfma_f32_16x16x32_bf16 v[130:133], v[2:5], v[46:49], 0
	v_mfma_f32_16x16x32_bf16 v[146:149], v[2:5], v[106:109], 0
	v_mfma_f32_16x16x32_bf16 v[154:157], v[2:5], v[114:117], 0
	v_mfma_f32_16x16x32_bf16 v[2:5], v[2:5], v[122:125], 0
	v_mfma_f32_16x16x32_bf16 v[130:133], v[6:9], v[102:105], v[130:133]
	v_mfma_f32_16x16x32_bf16 v[134:137], v[10:13], v[46:49], 0
	v_mfma_f32_16x16x32_bf16 v[146:149], v[6:9], v[110:113], v[146:149]
	v_mfma_f32_16x16x32_bf16 v[150:153], v[10:13], v[106:109], 0
	v_mfma_f32_16x16x32_bf16 v[154:157], v[6:9], v[118:121], v[154:157]
	v_mfma_f32_16x16x32_bf16 v[158:161], v[10:13], v[114:117], 0
	v_mfma_f32_16x16x32_bf16 v[2:5], v[6:9], v[126:129], v[2:5]
	v_mfma_f32_16x16x32_bf16 v[6:9], v[10:13], v[122:125], 0
	v_mfma_f32_16x16x32_bf16 v[134:137], v[14:17], v[102:105], v[134:137]
	v_mfma_f32_16x16x32_bf16 v[150:153], v[14:17], v[110:113], v[150:153]
	v_mfma_f32_16x16x32_bf16 v[158:161], v[14:17], v[118:121], v[158:161]
	v_mfma_f32_16x16x32_bf16 v[6:9], v[14:17], v[126:129], v[6:9]
	s_barrier
	s_add_u32 s52, s30, 0x10100
	s_addc_u32 s53, s31, 0
	s_add_i32 s48, s48, s38
	v_lshl_add_u64 v[10:11], s[52:53], 0, v[140:141]
	s_mov_b32 m0, s48
	s_add_i32 s46, s48, 0x2000
	global_load_lds_dwordx4 v[10:11], off
	v_lshl_add_u64 v[10:11], s[52:53], 0, v[144:145]
	s_mov_b32 m0, s46
	s_nop 0
	global_load_lds_dwordx4 v[10:11], off
	s_waitcnt vmcnt(6)
	s_barrier
	v_mfma_f32_16x16x32_bf16 v[10:13], v[82:85], v[46:49], 0
	v_mfma_f32_16x16x32_bf16 v[14:17], v[90:93], v[46:49], 0
	v_mfma_f32_16x16x32_bf16 v[10:13], v[86:89], v[102:105], v[10:13]
	v_mfma_f32_16x16x32_bf16 v[14:17], v[94:97], v[102:105], v[14:17]
	v_mfma_f32_16x16x32_bf16 v[46:49], v[82:85], v[106:109], 0
	v_mfma_f32_16x16x32_bf16 v[102:105], v[90:93], v[106:109], 0
	v_mfma_f32_16x16x32_bf16 v[106:109], v[82:85], v[114:117], 0
	v_mfma_f32_16x16x32_bf16 v[82:85], v[82:85], v[122:125], 0
	v_mfma_f32_16x16x32_bf16 v[46:49], v[86:89], v[110:113], v[46:49]
	v_mfma_f32_16x16x32_bf16 v[102:105], v[94:97], v[110:113], v[102:105]
	v_mfma_f32_16x16x32_bf16 v[106:109], v[86:89], v[118:121], v[106:109]
	v_mfma_f32_16x16x32_bf16 v[110:113], v[90:93], v[114:117], 0
	v_mfma_f32_16x16x32_bf16 v[82:85], v[86:89], v[126:129], v[82:85]
	v_mfma_f32_16x16x32_bf16 v[86:89], v[90:93], v[122:125], 0
	v_mfma_f32_16x16x32_bf16 v[110:113], v[94:97], v[118:121], v[110:113]
	v_mfma_f32_16x16x32_bf16 v[86:89], v[94:97], v[126:129], v[86:89]
	s_add_i32 s51, 0, 0x18000
	v_add_u32_e32 v232, s51, v1
	s_barrier
	ds_read_b128 v[90:93], v232
	ds_read_b128 v[94:97], v232 offset:1024
	ds_read_b128 v[114:117], v232 offset:2048
	ds_read_b128 v[118:121], v232 offset:3072
	s_add_u32 s52, s28, 0x40100
	s_addc_u32 s53, s29, 0
	s_mov_b32 m0, s40
	v_lshl_add_u64 v[202:203], s[52:53], 0, v[138:139]
	ds_read_b128 v[122:125], v172 offset:32768
	ds_read_b128 v[126:129], v172 offset:33792
	ds_read_b128 v[162:165], v172 offset:34816
	ds_read_b128 v[166:169], v172 offset:35840
	ds_read_b128 v[174:177], v172 offset:36864
	ds_read_b128 v[190:193], v172 offset:37888
	ds_read_b128 v[194:197], v172 offset:38912
	ds_read_b128 v[198:201], v172 offset:39936
	global_load_lds_dwordx4 v[202:203], off
	v_lshl_add_u64 v[202:203], s[52:53], 0, v[142:143]
	s_mov_b32 m0, s41
	s_nop 0
	global_load_lds_dwordx4 v[202:203], off
	s_waitcnt lgkmcnt(8)
	s_barrier
	s_waitcnt lgkmcnt(0)
	s_waitcnt lgkmcnt(0)
	v_mfma_f32_16x16x32_bf16 v[50:53], v[90:93], v[122:125], v[50:53]
	v_mfma_f32_16x16x32_bf16 v[54:57], v[114:117], v[122:125], v[54:57]
	v_mfma_f32_16x16x32_bf16 v[58:61], v[90:93], v[162:165], v[58:61]
	v_mfma_f32_16x16x32_bf16 v[62:65], v[114:117], v[162:165], v[62:65]
	v_mfma_f32_16x16x32_bf16 v[66:69], v[90:93], v[174:177], v[66:69]
	v_mfma_f32_16x16x32_bf16 v[70:73], v[114:117], v[174:177], v[70:73]
	v_mfma_f32_16x16x32_bf16 v[74:77], v[90:93], v[194:197], v[74:77]
	v_mfma_f32_16x16x32_bf16 v[78:81], v[114:117], v[194:197], v[78:81]
	v_mfma_f32_16x16x32_bf16 v[50:53], v[94:97], v[126:129], v[50:53]
	v_mfma_f32_16x16x32_bf16 v[54:57], v[118:121], v[126:129], v[54:57]
	v_mfma_f32_16x16x32_bf16 v[58:61], v[94:97], v[166:169], v[58:61]
	v_mfma_f32_16x16x32_bf16 v[62:65], v[118:121], v[166:169], v[62:65]
	v_mfma_f32_16x16x32_bf16 v[66:69], v[94:97], v[190:193], v[66:69]
	v_mfma_f32_16x16x32_bf16 v[70:73], v[118:121], v[190:193], v[70:73]
	v_mfma_f32_16x16x32_bf16 v[74:77], v[94:97], v[198:201], v[74:77]
	v_mfma_f32_16x16x32_bf16 v[78:81], v[118:121], v[198:201], v[78:81]
	s_barrier
	s_add_i32 s54, 0, 0x1c000
	s_mov_b64 s[52:53], 0x180
	s_add_i32 s51, s51, s38
	v_add_u32_e32 v233, s54, v1
	v_lshl_add_u64 v[170:171], v[170:171], 0, s[52:53]
	s_mov_b32 m0, s51
	s_add_i32 s49, s51, 0x2000
	ds_read_b128 v[202:205], v233
	ds_read_b128 v[206:209], v233 offset:1024
	ds_read_b128 v[210:213], v233 offset:2048
	ds_read_b128 v[214:217], v233 offset:3072
	global_load_lds_dwordx4 v[170:171], off
	v_lshl_add_u64 v[170:171], v[186:187], 0, s[52:53]
	s_mov_b32 m0, s49
	s_nop 0
	global_load_lds_dwordx4 v[170:171], off
	s_barrier
	s_waitcnt lgkmcnt(0)
	s_waitcnt lgkmcnt(0)
	v_mfma_f32_16x16x32_bf16 v[98:101], v[202:205], v[122:125], v[98:101]
	v_mfma_f32_16x16x32_bf16 v[18:21], v[210:213], v[122:125], v[18:21]
	v_mfma_f32_16x16x32_bf16 v[22:25], v[202:205], v[162:165], v[22:25]
	v_mfma_f32_16x16x32_bf16 v[26:29], v[210:213], v[162:165], v[26:29]
	v_mfma_f32_16x16x32_bf16 v[30:33], v[202:205], v[174:177], v[30:33]
	v_mfma_f32_16x16x32_bf16 v[34:37], v[210:213], v[174:177], v[34:37]
	v_mfma_f32_16x16x32_bf16 v[38:41], v[202:205], v[194:197], v[38:41]
	v_mfma_f32_16x16x32_bf16 v[42:45], v[210:213], v[194:197], v[42:45]
	v_mfma_f32_16x16x32_bf16 v[98:101], v[206:209], v[126:129], v[98:101]
	v_mfma_f32_16x16x32_bf16 v[18:21], v[214:217], v[126:129], v[18:21]
	v_mfma_f32_16x16x32_bf16 v[22:25], v[206:209], v[166:169], v[22:25]
	v_mfma_f32_16x16x32_bf16 v[26:29], v[214:217], v[166:169], v[26:29]
	v_mfma_f32_16x16x32_bf16 v[30:33], v[206:209], v[190:193], v[30:33]
	v_mfma_f32_16x16x32_bf16 v[34:37], v[214:217], v[190:193], v[34:37]
	v_mfma_f32_16x16x32_bf16 v[38:41], v[206:209], v[198:201], v[38:41]
	v_mfma_f32_16x16x32_bf16 v[42:45], v[214:217], v[198:201], v[42:45]
	s_mov_b32 m0, s42
	v_lshl_add_u64 v[170:171], v[188:189], 0, s[52:53]
	s_barrier
	ds_read_b128 v[122:125], v172 offset:49152
	ds_read_b128 v[126:129], v172 offset:50176
	ds_read_b128 v[162:165], v172 offset:51200
	ds_read_b128 v[166:169], v172 offset:52224
	ds_read_b128 v[174:177], v172 offset:53248
	ds_read_b128 v[190:193], v172 offset:54272
	ds_read_b128 v[194:197], v172 offset:55296
	ds_read_b128 v[198:201], v172 offset:56320
	global_load_lds_dwordx4 v[170:171], off
	v_lshl_add_u64 v[170:171], v[218:219], 0, s[52:53]
	s_mov_b32 m0, s43
	s_nop 0
	global_load_lds_dwordx4 v[170:171], off
	s_barrier
	s_waitcnt lgkmcnt(0)
	s_waitcnt lgkmcnt(0)
	v_mfma_f32_16x16x32_bf16 v[130:133], v[90:93], v[122:125], v[130:133]
	v_mfma_f32_16x16x32_bf16 v[134:137], v[114:117], v[122:125], v[134:137]
	v_mfma_f32_16x16x32_bf16 v[146:149], v[90:93], v[162:165], v[146:149]
	v_mfma_f32_16x16x32_bf16 v[150:153], v[114:117], v[162:165], v[150:153]
	v_mfma_f32_16x16x32_bf16 v[154:157], v[90:93], v[174:177], v[154:157]
	v_mfma_f32_16x16x32_bf16 v[158:161], v[114:117], v[174:177], v[158:161]
	v_mfma_f32_16x16x32_bf16 v[2:5], v[90:93], v[194:197], v[2:5]
	v_mfma_f32_16x16x32_bf16 v[6:9], v[114:117], v[194:197], v[6:9]
	v_mfma_f32_16x16x32_bf16 v[130:133], v[94:97], v[126:129], v[130:133]
	v_mfma_f32_16x16x32_bf16 v[134:137], v[118:121], v[126:129], v[134:137]
	v_mfma_f32_16x16x32_bf16 v[146:149], v[94:97], v[166:169], v[146:149]
	v_mfma_f32_16x16x32_bf16 v[150:153], v[118:121], v[166:169], v[150:153]
	v_mfma_f32_16x16x32_bf16 v[154:157], v[94:97], v[190:193], v[154:157]
	v_mfma_f32_16x16x32_bf16 v[158:161], v[118:121], v[190:193], v[158:161]
	v_mfma_f32_16x16x32_bf16 v[2:5], v[94:97], v[198:201], v[2:5]
	v_mfma_f32_16x16x32_bf16 v[6:9], v[118:121], v[198:201], v[6:9]
	s_barrier
	s_add_u32 s52, s30, 0x10180
	s_addc_u32 s53, s31, 0
	s_add_i32 s31, s54, s38
	v_lshl_add_u64 v[90:91], s[52:53], 0, v[140:141]
	s_mov_b32 m0, s31
	s_add_i32 s30, s31, 0x2000
	global_load_lds_dwordx4 v[90:91], off
	v_lshl_add_u64 v[90:91], s[52:53], 0, v[144:145]
	s_mov_b32 m0, s30
	s_nop 0
	global_load_lds_dwordx4 v[90:91], off
	s_waitcnt vmcnt(6)
	s_barrier
	v_mfma_f32_16x16x32_bf16 v[10:13], v[202:205], v[122:125], v[10:13]
	v_mfma_f32_16x16x32_bf16 v[14:17], v[210:213], v[122:125], v[14:17]
	v_mfma_f32_16x16x32_bf16 v[46:49], v[202:205], v[162:165], v[46:49]
	v_mfma_f32_16x16x32_bf16 v[90:93], v[210:213], v[162:165], v[102:105]
	v_mfma_f32_16x16x32_bf16 v[94:97], v[202:205], v[174:177], v[106:109]
	v_mfma_f32_16x16x32_bf16 v[102:105], v[210:213], v[174:177], v[110:113]
	v_mfma_f32_16x16x32_bf16 v[82:85], v[202:205], v[194:197], v[82:85]
	v_mfma_f32_16x16x32_bf16 v[86:89], v[210:213], v[194:197], v[86:89]
	v_mfma_f32_16x16x32_bf16 v[10:13], v[206:209], v[126:129], v[10:13]
	v_mfma_f32_16x16x32_bf16 v[14:17], v[214:217], v[126:129], v[14:17]
	v_mfma_f32_16x16x32_bf16 v[46:49], v[206:209], v[166:169], v[46:49]
	v_mfma_f32_16x16x32_bf16 v[90:93], v[214:217], v[166:169], v[90:93]
	v_mfma_f32_16x16x32_bf16 v[94:97], v[206:209], v[190:193], v[94:97]
	v_mfma_f32_16x16x32_bf16 v[102:105], v[214:217], v[190:193], v[102:105]
	v_mfma_f32_16x16x32_bf16 v[82:85], v[206:209], v[198:201], v[82:85]
	v_mfma_f32_16x16x32_bf16 v[86:89], v[214:217], v[198:201], v[86:89]
	s_barrier
	ds_read_b128 v[106:109], v173
	ds_read_b128 v[110:113], v173 offset:1024
	ds_read_b128 v[114:117], v173 offset:2048
	ds_read_b128 v[118:121], v173 offset:3072
	s_add_u32 s28, s28, 0x40180
	s_addc_u32 s29, s29, 0
	s_mov_b32 m0, s50
	v_lshl_add_u64 v[170:171], s[28:29], 0, v[138:139]
	ds_read_b128 v[122:125], v172
	ds_read_b128 v[126:129], v172 offset:1024
	ds_read_b128 v[162:165], v172 offset:2048
	ds_read_b128 v[166:169], v172 offset:3072
	ds_read_b128 v[174:177], v172 offset:4096
	ds_read_b128 v[190:193], v172 offset:5120
	ds_read_b128 v[194:197], v172 offset:6144
	ds_read_b128 v[198:201], v172 offset:7168
	global_load_lds_dwordx4 v[170:171], off
	v_lshl_add_u64 v[170:171], s[28:29], 0, v[142:143]
	s_mov_b32 m0, s21
	s_nop 0
	global_load_lds_dwordx4 v[170:171], off
	s_waitcnt lgkmcnt(8)
	s_barrier
	s_waitcnt lgkmcnt(0)
	s_waitcnt lgkmcnt(0)
	v_mfma_f32_16x16x32_bf16 v[58:61], v[106:109], v[162:165], v[58:61]
	v_mfma_f32_16x16x32_bf16 v[202:205], v[110:113], v[166:169], v[58:61]
	v_mfma_f32_16x16x32_bf16 v[58:61], v[114:117], v[162:165], v[62:65]
	v_mfma_f32_16x16x32_bf16 v[62:65], v[118:121], v[166:169], v[58:61]
	v_mfma_f32_16x16x32_bf16 v[58:61], v[106:109], v[174:177], v[66:69]
	v_mfma_f32_16x16x32_bf16 v[66:69], v[110:113], v[190:193], v[58:61]
	v_mfma_f32_16x16x32_bf16 v[58:61], v[114:117], v[174:177], v[70:73]
	v_mfma_f32_16x16x32_bf16 v[70:73], v[118:121], v[190:193], v[58:61]
	v_mfma_f32_16x16x32_bf16 v[58:61], v[106:109], v[194:197], v[74:77]
	v_mfma_f32_16x16x32_bf16 v[50:53], v[106:109], v[122:125], v[50:53]
	v_mfma_f32_16x16x32_bf16 v[54:57], v[114:117], v[122:125], v[54:57]
	v_mfma_f32_16x16x32_bf16 v[74:77], v[110:113], v[198:201], v[58:61]
	v_mfma_f32_16x16x32_bf16 v[58:61], v[114:117], v[194:197], v[78:81]
	v_mfma_f32_16x16x32_bf16 v[50:53], v[110:113], v[126:129], v[50:53]
	v_mfma_f32_16x16x32_bf16 v[54:57], v[118:121], v[126:129], v[54:57]
	v_mfma_f32_16x16x32_bf16 v[78:81], v[118:121], v[198:201], v[58:61]
	s_barrier
	s_mov_b32 m0, s47
	v_lshl_add_u64 v[170:171], s[6:7], 0, v[140:141]
	s_nop 0
	ds_read_b128 v[58:61], v220
	ds_read_b128 v[206:209], v220 offset:1024
	ds_read_b128 v[210:213], v220 offset:2048
	ds_read_b128 v[214:217], v220 offset:3072
	global_load_lds_dwordx4 v[170:171], off
	v_lshl_add_u64 v[230:231], s[6:7], 0, v[144:145]
	s_mov_b32 m0, s23
	s_nop 0
	global_load_lds_dwordx4 v[230:231], off
	s_barrier
	s_waitcnt lgkmcnt(0)
	s_waitcnt lgkmcnt(0)
	v_mfma_f32_16x16x32_bf16 v[34:37], v[210:213], v[174:177], v[34:37]
	v_mfma_f32_16x16x32_bf16 v[22:25], v[58:61], v[162:165], v[22:25]
	v_mfma_f32_16x16x32_bf16 v[26:29], v[210:213], v[162:165], v[26:29]
	v_mfma_f32_16x16x32_bf16 v[162:165], v[214:217], v[190:193], v[34:37]
	v_mfma_f32_16x16x32_bf16 v[34:37], v[58:61], v[194:197], v[38:41]
	v_mfma_f32_16x16x32_bf16 v[98:101], v[58:61], v[122:125], v[98:101]
	v_mfma_f32_16x16x32_bf16 v[18:21], v[210:213], v[122:125], v[18:21]
	v_mfma_f32_16x16x32_bf16 v[30:33], v[58:61], v[174:177], v[30:33]
	v_mfma_f32_16x16x32_bf16 v[38:41], v[206:209], v[198:201], v[34:37]
	v_mfma_f32_16x16x32_bf16 v[34:37], v[210:213], v[194:197], v[42:45]
	v_mfma_f32_16x16x32_bf16 v[98:101], v[206:209], v[126:129], v[98:101]
	v_mfma_f32_16x16x32_bf16 v[18:21], v[214:217], v[126:129], v[18:21]
	v_mfma_f32_16x16x32_bf16 v[22:25], v[206:209], v[166:169], v[22:25]
	v_mfma_f32_16x16x32_bf16 v[26:29], v[214:217], v[166:169], v[26:29]
	v_mfma_f32_16x16x32_bf16 v[30:33], v[206:209], v[190:193], v[30:33]
	v_mfma_f32_16x16x32_bf16 v[166:169], v[214:217], v[198:201], v[34:37]
	s_mov_b32 m0, s3
	v_lshl_add_u64 v[252:253], s[24:25], 0, v[138:139]
	s_barrier
	ds_read_b128 v[34:37], v172 offset:16384
	ds_read_b128 v[42:45], v172 offset:17408
	ds_read_b128 v[122:125], v172 offset:18432
	ds_read_b128 v[126:129], v172 offset:19456
	ds_read_b128 v[174:177], v172 offset:20480
	ds_read_b128 v[190:193], v172 offset:21504
	ds_read_b128 v[194:197], v172 offset:22528
	ds_read_b128 v[198:201], v172 offset:23552
	global_load_lds_dwordx4 v[252:253], off
	v_lshl_add_u64 v[246:247], s[24:25], 0, v[142:143]
	s_mov_b32 m0, s39
	s_nop 0
	global_load_lds_dwordx4 v[246:247], off
	s_barrier
	s_waitcnt lgkmcnt(0)
	s_waitcnt lgkmcnt(0)
	v_mfma_f32_16x16x32_bf16 v[130:133], v[106:109], v[34:37], v[130:133]
	v_mfma_f32_16x16x32_bf16 v[218:221], v[110:113], v[42:45], v[130:133]
	v_mfma_f32_16x16x32_bf16 v[130:133], v[114:117], v[34:37], v[134:137]
	v_mfma_f32_16x16x32_bf16 v[222:225], v[118:121], v[42:45], v[130:133]
	v_mfma_f32_16x16x32_bf16 v[130:133], v[106:109], v[122:125], v[146:149]
	v_mfma_f32_16x16x32_bf16 v[146:149], v[110:113], v[126:129], v[130:133]
	v_mfma_f32_16x16x32_bf16 v[130:133], v[114:117], v[122:125], v[150:153]
	v_mfma_f32_16x16x32_bf16 v[150:153], v[118:121], v[126:129], v[130:133]
	v_mfma_f32_16x16x32_bf16 v[130:133], v[106:109], v[174:177], v[154:157]
	v_mfma_f32_16x16x32_bf16 v[154:157], v[110:113], v[190:193], v[130:133]
	v_mfma_f32_16x16x32_bf16 v[130:133], v[114:117], v[174:177], v[158:161]
	v_mfma_f32_16x16x32_bf16 v[2:5], v[106:109], v[194:197], v[2:5]
	v_mfma_f32_16x16x32_bf16 v[6:9], v[114:117], v[194:197], v[6:9]
	v_mfma_f32_16x16x32_bf16 v[158:161], v[118:121], v[190:193], v[130:133]
	v_mfma_f32_16x16x32_bf16 v[2:5], v[110:113], v[198:201], v[2:5]
	v_mfma_f32_16x16x32_bf16 v[6:9], v[118:121], v[198:201], v[6:9]
	s_barrier
	s_add_u32 s28, s6, 0x10000
	s_addc_u32 s29, s7, 0
	s_mov_b32 m0, s48
	v_lshl_add_u64 v[106:107], s[28:29], 0, v[140:141]
	global_load_lds_dwordx4 v[106:107], off
	v_lshl_add_u64 v[106:107], s[28:29], 0, v[144:145]
	s_mov_b32 m0, s46
	s_nop 0
	global_load_lds_dwordx4 v[106:107], off
	s_waitcnt vmcnt(6)
	s_barrier
	v_mfma_f32_16x16x32_bf16 v[10:13], v[58:61], v[34:37], v[10:13]
	v_mfma_f32_16x16x32_bf16 v[226:229], v[206:209], v[42:45], v[10:13]
	v_mfma_f32_16x16x32_bf16 v[10:13], v[210:213], v[34:37], v[14:17]
	v_mfma_f32_16x16x32_bf16 v[14:17], v[214:217], v[42:45], v[10:13]
	v_mfma_f32_16x16x32_bf16 v[10:13], v[58:61], v[122:125], v[46:49]
	v_mfma_f32_16x16x32_bf16 v[248:251], v[206:209], v[126:129], v[10:13]
	v_mfma_f32_16x16x32_bf16 v[10:13], v[210:213], v[122:125], v[90:93]
	v_mfma_f32_16x16x32_bf16 v[236:239], v[214:217], v[126:129], v[10:13]
	v_mfma_f32_16x16x32_bf16 v[10:13], v[58:61], v[174:177], v[94:97]
	v_mfma_f32_16x16x32_bf16 v[186:189], v[206:209], v[190:193], v[10:13]
	v_mfma_f32_16x16x32_bf16 v[10:13], v[210:213], v[174:177], v[102:105]
	v_mfma_f32_16x16x32_bf16 v[174:177], v[214:217], v[190:193], v[10:13]
	v_mfma_f32_16x16x32_bf16 v[10:13], v[58:61], v[194:197], v[82:85]
	v_mfma_f32_16x16x32_bf16 v[190:193], v[206:209], v[198:201], v[10:13]
	v_mfma_f32_16x16x32_bf16 v[10:13], v[210:213], v[194:197], v[86:89]
	v_mfma_f32_16x16x32_bf16 v[194:197], v[214:217], v[198:201], v[10:13]
	s_barrier
	ds_read_b128 v[86:89], v232
	ds_read_b128 v[94:97], v232 offset:1024
	ds_read_b128 v[102:105], v232 offset:2048
	ds_read_b128 v[198:201], v232 offset:3072
	s_add_u32 s28, s24, 0x40000
	s_addc_u32 s29, s25, 0
	s_mov_b32 m0, s40
	v_lshl_add_u64 v[34:35], s[28:29], 0, v[138:139]
	ds_read_b128 v[10:13], v172 offset:32768
	ds_read_b128 v[46:49], v172 offset:33792
	ds_read_b128 v[82:85], v172 offset:34816
	ds_read_b128 v[90:93], v172 offset:35840
	ds_read_b128 v[110:113], v172 offset:36864
	ds_read_b128 v[206:209], v172 offset:37888
	ds_read_b128 v[210:213], v172 offset:38912
	ds_read_b128 v[214:217], v172 offset:39936
	global_load_lds_dwordx4 v[34:35], off
	v_lshl_add_u64 v[34:35], s[28:29], 0, v[142:143]
	s_mov_b32 m0, s41
	s_nop 0
	global_load_lds_dwordx4 v[34:35], off
	s_waitcnt lgkmcnt(8)
	s_barrier
	s_waitcnt lgkmcnt(0)
	s_waitcnt lgkmcnt(0)
	v_mfma_f32_16x16x32_bf16 v[34:37], v[86:89], v[10:13], v[50:53]
	v_mfma_f32_16x16x32_bf16 v[130:133], v[94:97], v[46:49], v[34:37]
	v_mfma_f32_16x16x32_bf16 v[34:37], v[102:105], v[10:13], v[54:57]
	v_mfma_f32_16x16x32_bf16 v[58:61], v[198:201], v[46:49], v[34:37]
	v_mfma_f32_16x16x32_bf16 v[34:37], v[86:89], v[82:85], v[202:205]
	v_mfma_f32_16x16x32_bf16 v[122:125], v[94:97], v[90:93], v[34:37]
	v_mfma_f32_16x16x32_bf16 v[34:37], v[102:105], v[82:85], v[62:65]
	v_mfma_f32_16x16x32_bf16 v[50:53], v[198:201], v[90:93], v[34:37]
	v_mfma_f32_16x16x32_bf16 v[34:37], v[86:89], v[110:113], v[66:69]
	v_mfma_f32_16x16x32_bf16 v[114:117], v[94:97], v[206:209], v[34:37]
	v_mfma_f32_16x16x32_bf16 v[34:37], v[102:105], v[110:113], v[70:73]
	v_mfma_f32_16x16x32_bf16 v[42:45], v[198:201], v[206:209], v[34:37]
	v_mfma_f32_16x16x32_bf16 v[34:37], v[86:89], v[210:213], v[74:77]
	v_mfma_f32_16x16x32_bf16 v[106:109], v[94:97], v[214:217], v[34:37]
	v_mfma_f32_16x16x32_bf16 v[34:37], v[102:105], v[210:213], v[78:81]
	v_mfma_f32_16x16x32_bf16 v[34:37], v[198:201], v[214:217], v[34:37]
	s_barrier
	s_mov_b32 m0, s51
	v_lshl_add_u64 v[54:55], v[170:171], 0, s[0:1]
	ds_read_b128 v[70:73], v233
	ds_read_b128 v[74:77], v233 offset:1024
	ds_read_b128 v[78:81], v233 offset:2048
	ds_read_b128 v[202:205], v233 offset:3072
	global_load_lds_dwordx4 v[54:55], off
	v_lshl_add_u64 v[54:55], v[230:231], 0, s[0:1]
	s_mov_b32 m0, s49
	s_nop 0
	global_load_lds_dwordx4 v[54:55], off
	s_barrier
	s_waitcnt lgkmcnt(0)
	s_waitcnt lgkmcnt(0)
	v_mfma_f32_16x16x32_bf16 v[54:57], v[70:73], v[10:13], v[98:101]
	v_mfma_f32_16x16x32_bf16 v[10:13], v[78:81], v[10:13], v[18:21]
	v_mfma_f32_16x16x32_bf16 v[62:65], v[202:205], v[46:49], v[10:13]
	v_mfma_f32_16x16x32_bf16 v[10:13], v[70:73], v[82:85], v[22:25]
	v_mfma_f32_16x16x32_bf16 v[126:129], v[74:77], v[90:93], v[10:13]
	v_mfma_f32_16x16x32_bf16 v[10:13], v[78:81], v[82:85], v[26:29]
	v_mfma_f32_16x16x32_bf16 v[134:137], v[74:77], v[46:49], v[54:57]
	v_mfma_f32_16x16x32_bf16 v[54:57], v[202:205], v[90:93], v[10:13]
	v_mfma_f32_16x16x32_bf16 v[10:13], v[70:73], v[110:113], v[30:33]
	v_mfma_f32_16x16x32_bf16 v[118:121], v[74:77], v[206:209], v[10:13]
	v_mfma_f32_16x16x32_bf16 v[10:13], v[78:81], v[110:113], v[162:165]
	v_mfma_f32_16x16x32_bf16 v[46:49], v[202:205], v[206:209], v[10:13]
	v_mfma_f32_16x16x32_bf16 v[10:13], v[70:73], v[210:213], v[38:41]
	v_mfma_f32_16x16x32_bf16 v[110:113], v[74:77], v[214:217], v[10:13]
	v_mfma_f32_16x16x32_bf16 v[10:13], v[78:81], v[210:213], v[166:169]
	v_mfma_f32_16x16x32_bf16 v[38:41], v[202:205], v[214:217], v[10:13]
	s_mov_b32 m0, s42
	s_nop 4
	v_lshl_add_u64 v[10:11], v[252:253], 0, s[0:1]
	s_barrier
	ds_read_b128 v[22:25], v172 offset:49152
	ds_read_b128 v[30:33], v172 offset:50176
	ds_read_b128 v[162:165], v172 offset:51200
	ds_read_b128 v[166:169], v172 offset:52224
	ds_read_b128 v[206:209], v172 offset:53248
	ds_read_b128 v[210:213], v172 offset:54272
	ds_read_b128 v[214:217], v172 offset:55296
	ds_read_b128 v[230:233], v172 offset:56320
	global_load_lds_dwordx4 v[10:11], off
	v_lshl_add_u64 v[10:11], v[246:247], 0, s[0:1]
	s_mov_b32 m0, s43
	s_nop 0
	global_load_lds_dwordx4 v[10:11], off
	s_barrier
	s_waitcnt lgkmcnt(0)
	s_waitcnt lgkmcnt(0)
	v_mfma_f32_16x16x32_bf16 v[10:13], v[86:89], v[22:25], v[218:221]
	v_mfma_f32_16x16x32_bf16 v[98:101], v[94:97], v[30:33], v[10:13]
	v_mfma_f32_16x16x32_bf16 v[10:13], v[102:105], v[22:25], v[222:225]
	v_mfma_f32_16x16x32_bf16 v[26:29], v[198:201], v[30:33], v[10:13]
	v_mfma_f32_16x16x32_bf16 v[10:13], v[86:89], v[162:165], v[146:149]
	v_mfma_f32_16x16x32_bf16 v[90:93], v[94:97], v[166:169], v[10:13]
	v_mfma_f32_16x16x32_bf16 v[10:13], v[102:105], v[162:165], v[150:153]
	v_mfma_f32_16x16x32_bf16 v[18:21], v[198:201], v[166:169], v[10:13]
	v_mfma_f32_16x16x32_bf16 v[10:13], v[86:89], v[206:209], v[154:157]
	v_mfma_f32_16x16x32_bf16 v[2:5], v[86:89], v[214:217], v[2:5]
	v_mfma_f32_16x16x32_bf16 v[82:85], v[94:97], v[210:213], v[10:13]
	v_mfma_f32_16x16x32_bf16 v[10:13], v[102:105], v[206:209], v[158:161]
	v_mfma_f32_16x16x32_bf16 v[66:69], v[94:97], v[230:233], v[2:5]
	v_mfma_f32_16x16x32_bf16 v[2:5], v[102:105], v[214:217], v[6:9]
	v_mfma_f32_16x16x32_bf16 v[10:13], v[198:201], v[210:213], v[10:13]
	v_mfma_f32_16x16x32_bf16 v[2:5], v[198:201], v[230:233], v[2:5]
	s_barrier
	s_add_u32 s6, s6, 0x10080
	s_addc_u32 s7, s7, 0
	s_mov_b32 m0, s31
	v_lshl_add_u64 v[6:7], s[6:7], 0, v[140:141]
	global_load_lds_dwordx4 v[6:7], off
	v_lshl_add_u64 v[6:7], s[6:7], 0, v[144:145]
	s_mov_b32 m0, s30
	s_nop 0
	global_load_lds_dwordx4 v[6:7], off
	s_waitcnt vmcnt(6)
	s_barrier
	v_mfma_f32_16x16x32_bf16 v[6:9], v[70:73], v[22:25], v[226:229]
	v_mfma_f32_16x16x32_bf16 v[102:105], v[74:77], v[30:33], v[6:9]
	v_mfma_f32_16x16x32_bf16 v[6:9], v[78:81], v[22:25], v[14:17]
	v_mfma_f32_16x16x32_bf16 v[30:33], v[202:205], v[30:33], v[6:9]
	v_mfma_f32_16x16x32_bf16 v[6:9], v[70:73], v[162:165], v[248:251]
	v_mfma_f32_16x16x32_bf16 v[94:97], v[74:77], v[166:169], v[6:9]
	v_mfma_f32_16x16x32_bf16 v[6:9], v[78:81], v[162:165], v[236:239]
	v_mfma_f32_16x16x32_bf16 v[22:25], v[202:205], v[166:169], v[6:9]
	v_mfma_f32_16x16x32_bf16 v[6:9], v[70:73], v[206:209], v[186:189]
	v_mfma_f32_16x16x32_bf16 v[86:89], v[74:77], v[210:213], v[6:9]
	v_mfma_f32_16x16x32_bf16 v[6:9], v[78:81], v[206:209], v[174:177]
	v_mfma_f32_16x16x32_bf16 v[14:17], v[202:205], v[210:213], v[6:9]
	v_mfma_f32_16x16x32_bf16 v[6:9], v[70:73], v[214:217], v[190:193]
	v_mfma_f32_16x16x32_bf16 v[70:73], v[74:77], v[230:233], v[6:9]
	v_mfma_f32_16x16x32_bf16 v[6:9], v[78:81], v[214:217], v[194:197]
	v_mfma_f32_16x16x32_bf16 v[6:9], v[202:205], v[230:233], v[6:9]
	v_mov_b32_e32 v74, v178
	s_barrier
	s_add_i32 s45, s45, s34
	v_ashrrev_i32_e32 v75, 2, v74
	v_and_b32_e32 v75, 0xffffffc0, v75
	v_lshl_add_u32 v75, s2, 8, v75
	v_and_or_b32 v148, v74, 15, v75
	v_lshrrev_b32_e32 v74, 1, v74
	v_and_b32_e32 v74, 0x78, v74
	v_lshl_or_b32 v150, s33, 7, v74
	v_ashrrev_i32_e32 v151, 31, v150
	v_lshlrev_b64 v[146:147], 2, v[150:151]
	v_lshl_add_u64 v[154:155], s[10:11], 0, v[146:147]
	global_load_dwordx4 v[158:161], v[154:155], off
	v_lshl_add_u64 v[152:153], s[16:17], 0, v[146:147]
	v_lshl_add_u64 v[156:157], s[8:9], 0, v[146:147]
	global_load_dwordx4 v[78:81], v[152:153], off
	global_load_dwordx4 v[74:77], v[156:157], off
	v_mov_b32_e32 v166, v148
	s_mov_b32 s2, 0xc1000000
	v_ashrrev_i32_e32 v167, 31, v166
	s_mov_b32 s33, s20
	s_mov_b64 s[30:31], s[26:27]
	s_mov_b64 s[28:29], s[24:25]
	s_waitcnt vmcnt(0)
	v_max_f32_e64 v146, -v158, -v158
	v_max_f32_e32 v162, 0, v146
	v_mul_f32_e64 v146, |v158|, s72
	v_exp_f32_e32 v146, v146
	v_add_f32_e32 v130, v130, v78
	v_add_f32_e32 v131, v131, v79
	v_mul_f32_e32 v130, 0xbfb8aa3b, v130
	v_add_f32_e32 v146, 1.0, v146
	v_cmp_gt_f32_e32 vcc, s71, v146
	v_mul_f32_e32 v131, 0xbfb8aa3b, v131
	v_exp_f32_e32 v130, v130
	v_cndmask_b32_e64 v147, 0, 32, vcc
	v_ldexp_f32 v146, v146, v147
	v_log_f32_e32 v146, v146
	v_exp_f32_e32 v131, v131
	v_add_f32_e32 v130, 1.0, v130
	v_rcp_f32_e32 v170, v130
	v_mul_f32_e32 v147, 0x3f317217, v146
	v_fma_f32 v147, v146, s73, -v147
	v_fmac_f32_e32 v147, 0x3377d1cf, v146
	v_fmac_f32_e32 v147, 0x3f317217, v146
	v_cmp_lt_f32_e64 s[6:7], |v146|, s74
	v_add_f32_e32 v131, 1.0, v131
	v_rcp_f32_e32 v171, v131
	v_cndmask_b32_e64 v146, v146, v147, s[6:7]
	v_cndmask_b32_e32 v147, 0, v243, vcc
	v_sub_f32_e32 v164, v146, v147
	v_max_f32_e64 v146, -v159, -v159
	v_max_f32_e32 v163, 0, v146
	v_mul_f32_e64 v146, |v159|, s72
	v_exp_f32_e32 v146, v146
	v_add_f32_e32 v130, v134, v74
	v_add_f32_e32 v131, v135, v75
	v_mul_f32_e32 v130, 0xbfb8aa3b, v130
	v_add_f32_e32 v146, 1.0, v146
	v_cmp_gt_f32_e32 vcc, s71, v146
	v_mul_f32_e32 v131, 0xbfb8aa3b, v131
	v_exp_f32_e32 v130, v130
	v_cndmask_b32_e64 v147, 0, 32, vcc
	v_ldexp_f32 v146, v146, v147
	v_log_f32_e32 v146, v146
	v_exp_f32_e32 v131, v131
	v_add_f32_e32 v130, 1.0, v130
	v_rcp_f32_e32 v130, v130
	v_mul_f32_e32 v147, 0x3f317217, v146
	v_fma_f32 v147, v146, s73, -v147
	v_fmac_f32_e32 v147, 0x3377d1cf, v146
	v_fmac_f32_e32 v147, 0x3f317217, v146
	v_cmp_lt_f32_e64 s[6:7], |v146|, s74
	v_add_f32_e32 v131, 1.0, v131
	v_rcp_f32_e32 v131, v131
	v_cndmask_b32_e64 v146, v146, v147, s[6:7]
	v_cndmask_b32_e32 v147, 0, v243, vcc
	v_sub_f32_e32 v165, v146, v147
	v_max_f32_e64 v146, -v160, -v160
	v_max_f32_e32 v158, 0, v146
	v_mul_f32_e64 v146, |v160|, s72
	v_exp_f32_e32 v146, v146
	v_pk_add_f32 v[134:135], v[162:163], v[164:165]
	v_add_f32_e32 v122, v122, v78
	v_pk_mul_f32 v[134:135], v[134:135], s[2:3] op_sel_hi:[1,0]
	v_add_f32_e32 v146, 1.0, v146
	v_cmp_gt_f32_e32 vcc, s71, v146
	v_pk_mul_f32 v[162:163], v[170:171], v[134:135]
	v_add_f32_e32 v123, v123, v79
	v_cndmask_b32_e64 v147, 0, 32, vcc
	v_ldexp_f32 v146, v146, v147
	v_log_f32_e32 v146, v146
	v_add_f32_e32 v149, v162, v162
	v_mul_f32_e32 v149, 0x3fb8aa3b, v149
	v_exp_f32_e32 v149, v149
	v_mul_f32_e32 v147, 0x3f317217, v146
	v_fma_f32 v147, v146, s73, -v147
	v_fmac_f32_e32 v147, 0x3377d1cf, v146
	v_fmac_f32_e32 v147, 0x3f317217, v146
	v_cmp_lt_f32_e64 s[6:7], |v146|, s74
	v_sub_f32_e32 v149, 1.0, v149
	v_max_f32_e32 v149, 0, v149
	v_cndmask_b32_e64 v146, v146, v147, s[6:7]
	v_cndmask_b32_e32 v147, 0, v243, vcc
	v_sub_f32_e32 v160, v146, v147
	v_max_f32_e64 v146, -v161, -v161
	v_max_f32_e32 v159, 0, v146
	v_mul_f32_e64 v146, |v161|, s72
	v_exp_f32_e32 v146, v146
	v_sqrt_f32_e32 v164, v149
	v_add_f32_e32 v149, v163, v163
	v_mul_f32_e32 v149, 0x3fb8aa3b, v149
	v_add_f32_e32 v146, 1.0, v146
	v_cmp_gt_f32_e32 vcc, s71, v146
	v_exp_f32_e32 v149, v149
	v_mul_f32_e32 v122, 0xbfb8aa3b, v122
	v_cndmask_b32_e64 v147, 0, 32, vcc
	v_ldexp_f32 v146, v146, v147
	v_log_f32_e32 v146, v146
	v_sub_f32_e32 v149, 1.0, v149
	v_max_f32_e32 v149, 0, v149
	v_sqrt_f32_e32 v165, v149
	v_mul_f32_e32 v147, 0x3f317217, v146
	v_fma_f32 v147, v146, s73, -v147
	v_fmac_f32_e32 v147, 0x3377d1cf, v146
	v_fmac_f32_e32 v147, 0x3f317217, v146
	v_cmp_lt_f32_e64 s[6:7], |v146|, s74
	v_pk_mul_f32 v[130:131], v[130:131], v[164:165]
	v_mul_f32_e32 v123, 0xbfb8aa3b, v123
	v_cndmask_b32_e64 v146, v146, v147, s[6:7]
	v_cndmask_b32_e32 v147, 0, v243, vcc
	v_sub_f32_e32 v161, v146, v147
	v_lshlrev_b64 v[146:147], 11, v[166:167]
	v_lshl_add_u64 v[168:169], s[14:15], 0, v[146:147]
	v_lshlrev_b64 v[146:147], 1, v[150:151]
	v_lshl_add_u64 v[168:169], v[168:169], 0, v[146:147]
	v_mov_b32_e32 v230, v168
	v_mov_b32_e32 v231, v169
	v_mov_b32_e32 v232, 0x8000
	v_mov_b32_e32 v233, 0
	global_load_dwordx2 v[174:175], v[230:231], off
	global_load_dwordx2 v[202:203], v[230:231], off offset:8
	v_lshl_add_u64 v[230:231], v[230:231], 0, v[232:233]
	global_load_dwordx2 v[176:177], v[230:231], off
	global_load_dwordx2 v[204:205], v[230:231], off offset:8
	v_lshl_add_u64 v[230:231], v[230:231], 0, v[232:233]
	global_load_dwordx2 v[190:191], v[230:231], off
	global_load_dwordx2 v[206:207], v[230:231], off offset:8
	v_lshl_add_u64 v[230:231], v[230:231], 0, v[232:233]
	global_load_dwordx2 v[192:193], v[230:231], off
	global_load_dwordx2 v[208:209], v[230:231], off offset:8
	v_mov_b32_e32 v232, 0x28000
	v_lshl_add_u64 v[230:231], v[230:231], 0, v[232:233]
	v_mov_b32_e32 v232, 0x8000
	global_load_dwordx2 v[194:195], v[230:231], off
	global_load_dwordx2 v[210:211], v[230:231], off offset:8
	v_lshl_add_u64 v[230:231], v[230:231], 0, v[232:233]
	global_load_dwordx2 v[196:197], v[230:231], off
	global_load_dwordx2 v[212:213], v[230:231], off offset:8
	v_lshl_add_u64 v[230:231], v[230:231], 0, v[232:233]
	global_load_dwordx2 v[198:199], v[230:231], off
	global_load_dwordx2 v[214:215], v[230:231], off offset:8
	v_lshl_add_u64 v[230:231], v[230:231], 0, v[232:233]
	global_load_dwordx2 v[200:201], v[230:231], off
	global_load_dwordx2 v[216:217], v[230:231], off offset:8
	v_exp_f32_e32 v122, v122
	v_exp_f32_e32 v123, v123
	v_add_f32_e32 v126, v126, v74
	v_add_f32_e32 v127, v127, v75
	v_add_f32_e32 v122, 1.0, v122
	v_add_f32_e32 v123, 1.0, v123
	v_rcp_f32_e32 v122, v122
	v_rcp_f32_e32 v123, v123
	v_mul_f32_e32 v126, 0xbfb8aa3b, v126
	v_mul_f32_e32 v127, 0xbfb8aa3b, v127
	v_exp_f32_e32 v126, v126
	v_exp_f32_e32 v127, v127
	v_add_f32_e32 v114, v114, v78
	v_add_f32_e32 v115, v115, v79
	v_add_f32_e32 v126, 1.0, v126
	v_add_f32_e32 v127, 1.0, v127
	v_rcp_f32_e32 v126, v126
	v_rcp_f32_e32 v127, v127
	v_mul_f32_e32 v114, 0xbfb8aa3b, v114
	v_mul_f32_e32 v115, 0xbfb8aa3b, v115
	v_exp_f32_e32 v114, v114
	v_exp_f32_e32 v115, v115
	v_add_f32_e32 v118, v118, v74
	v_add_f32_e32 v119, v119, v75
	v_add_f32_e32 v114, 1.0, v114
	v_add_f32_e32 v115, 1.0, v115
	v_rcp_f32_e32 v114, v114
	v_rcp_f32_e32 v115, v115
	v_mul_f32_e32 v118, 0xbfb8aa3b, v118
	v_mul_f32_e32 v119, 0xbfb8aa3b, v119
	v_exp_f32_e32 v118, v118
	v_exp_f32_e32 v119, v119
	v_add_f32_e32 v106, v106, v78
	v_add_f32_e32 v107, v107, v79
	v_add_f32_e32 v118, 1.0, v118
	v_add_f32_e32 v119, 1.0, v119
	v_rcp_f32_e32 v118, v118
	v_rcp_f32_e32 v119, v119
	v_mul_f32_e32 v106, 0xbfb8aa3b, v106
	v_mul_f32_e32 v107, 0xbfb8aa3b, v107
	v_exp_f32_e32 v106, v106
	v_exp_f32_e32 v107, v107
	v_add_f32_e32 v110, v110, v74
	v_add_f32_e32 v111, v111, v75
	v_add_f32_e32 v106, 1.0, v106
	v_add_f32_e32 v107, 1.0, v107
	v_rcp_f32_e32 v106, v106
	v_rcp_f32_e32 v107, v107
	v_mul_f32_e32 v110, 0xbfb8aa3b, v110
	v_mul_f32_e32 v111, 0xbfb8aa3b, v111
	v_exp_f32_e32 v110, v110
	v_exp_f32_e32 v111, v111
	v_add_f32_e32 v98, v98, v78
	v_add_f32_e32 v99, v99, v79
	v_add_f32_e32 v110, 1.0, v110
	v_add_f32_e32 v111, 1.0, v111
	v_rcp_f32_e32 v110, v110
	v_rcp_f32_e32 v111, v111
	v_mul_f32_e32 v98, 0xbfb8aa3b, v98
	v_mul_f32_e32 v99, 0xbfb8aa3b, v99
	v_exp_f32_e32 v98, v98
	v_exp_f32_e32 v99, v99
	v_add_f32_e32 v102, v102, v74
	v_add_f32_e32 v103, v103, v75
	v_add_f32_e32 v98, 1.0, v98
	v_add_f32_e32 v99, 1.0, v99
	v_rcp_f32_e32 v98, v98
	v_rcp_f32_e32 v99, v99
	v_mul_f32_e32 v102, 0xbfb8aa3b, v102
	v_mul_f32_e32 v103, 0xbfb8aa3b, v103
	v_exp_f32_e32 v102, v102
	v_exp_f32_e32 v103, v103
	v_add_f32_e32 v90, v90, v78
	v_add_f32_e32 v91, v91, v79
	v_add_f32_e32 v102, 1.0, v102
	v_add_f32_e32 v103, 1.0, v103
	v_rcp_f32_e32 v102, v102
	v_rcp_f32_e32 v103, v103
	v_mul_f32_e32 v90, 0xbfb8aa3b, v90
	s_waitcnt vmcnt(0)
	v_mov_b32_e32 v168, v174
	v_mov_b32_e32 v169, v175
	v_lshlrev_b32_e32 v170, 16, v168
	v_and_b32_e32 v171, 0xffff0000, v168
	v_pk_mul_f32 v[164:165], v[130:131], v[170:171]
	v_add_f32_e32 v131, v136, v76
	v_mul_f32_e32 v131, 0xbfb8aa3b, v131
	v_exp_f32_e32 v131, v131
	v_add_f32_e32 v130, v132, v80
	v_mul_f32_e32 v130, 0xbfb8aa3b, v130
	v_exp_f32_e32 v130, v130
	v_add_f32_e32 v131, 1.0, v131
	v_rcp_f32_e32 v136, v131
	v_add_f32_e32 v131, v133, v81
	v_mul_f32_e32 v131, 0xbfb8aa3b, v131
	v_exp_f32_e32 v131, v131
	v_add_f32_e32 v132, v137, v77
	v_mul_f32_e32 v132, 0xbfb8aa3b, v132
	v_exp_f32_e32 v132, v132
	v_add_f32_e32 v130, 1.0, v130
	v_add_f32_e32 v131, 1.0, v131
	v_rcp_f32_e32 v130, v130
	v_rcp_f32_e32 v131, v131
	v_add_f32_e32 v132, 1.0, v132
	v_rcp_f32_e32 v137, v132
	v_pk_add_f32 v[132:133], v[158:159], v[160:161]
	v_lshlrev_b32_e32 v160, 16, v169
	v_pk_mul_f32 v[132:133], v[132:133], s[2:3] op_sel_hi:[1,0]
	v_and_b32_e32 v161, 0xffff0000, v169
	v_pk_mul_f32 v[130:131], v[130:131], v[132:133]
	v_mul_f32_e32 v91, 0xbfb8aa3b, v91
	v_add_f32_e32 v149, v130, v130
	v_mul_f32_e32 v149, 0x3fb8aa3b, v149
	v_exp_f32_e32 v149, v149
	v_exp_f32_e32 v90, v90
	v_exp_f32_e32 v91, v91
	v_add_f32_e32 v94, v94, v74
	v_sub_f32_e32 v149, 1.0, v149
	v_max_f32_e32 v149, 0, v149
	v_sqrt_f32_e32 v158, v149
	v_add_f32_e32 v149, v131, v131
	v_mul_f32_e32 v149, 0x3fb8aa3b, v149
	v_exp_f32_e32 v149, v149
	v_add_f32_e32 v90, 1.0, v90
	v_add_f32_e32 v91, 1.0, v91
	v_rcp_f32_e32 v90, v90
	v_sub_f32_e32 v149, 1.0, v149
	v_max_f32_e32 v149, 0, v149
	v_sqrt_f32_e32 v159, v149
	v_rcp_f32_e32 v91, v91
	v_add_f32_e32 v95, v95, v75
	v_mul_f32_e32 v94, 0xbfb8aa3b, v94
	v_pk_mul_f32 v[136:137], v[136:137], v[158:159]
	v_mul_f32_e32 v95, 0xbfb8aa3b, v95
	v_pk_mul_f32 v[158:159], v[136:137], v[160:161]
	v_cvt_pk_bf16_f32 v161, v130, v131
	v_mov_b64_e32 v[130:131], s[18:19]
	v_cvt_pk_bf16_f32 v160, v162, v163
	v_mad_i64_i32 v[162:163], s[6:7], v166, s84, v[130:131]
	v_lshl_add_u64 v[162:163], v[162:163], 0, v[146:147]
	v_add_co_u32_e32 v162, vcc, s69, v162
	v_add_u32_e32 v136, 16, v166
	s_nop 0
	v_addc_co_u32_e32 v163, vcc, 0, v163, vcc
	v_mov_b32_e32 v220, v160
	v_mov_b32_e32 v221, v161
	v_cvt_pk_bf16_f32 v160, v164, v165
	v_cvt_pk_bf16_f32 v161, v158, v159
	v_mov_b32_e32 v224, v160
	v_mov_b32_e32 v225, v161
	v_pk_mul_f32 v[160:161], v[122:123], v[134:135]
	v_ashrrev_i32_e32 v137, 31, v136
	v_lshlrev_b64 v[158:159], 11, v[136:137]
	v_lshl_add_u64 v[158:159], s[14:15], 0, v[158:159]
	v_lshl_add_u64 v[158:159], v[158:159], 0, v[146:147]
	s_nop 0
	v_add_f32_e32 v122, v160, v160
	v_add_f32_e32 v123, v161, v161
	v_mul_f32_e32 v122, 0x3fb8aa3b, v122
	v_mul_f32_e32 v123, 0x3fb8aa3b, v123
	v_exp_f32_e32 v122, v122
	v_exp_f32_e32 v123, v123
	v_exp_f32_e32 v94, v94
	v_exp_f32_e32 v95, v95
	v_sub_f32_e32 v122, 1.0, v122
	v_sub_f32_e32 v123, 1.0, v123
	v_max_f32_e32 v122, 0, v122
	v_max_f32_e32 v123, 0, v123
	v_sqrt_f32_e32 v122, v122
	v_sqrt_f32_e32 v123, v123
	v_add_f32_e32 v94, 1.0, v94
	v_add_f32_e32 v95, 1.0, v95
	v_rcp_f32_e32 v94, v94
	v_pk_mul_f32 v[122:123], v[126:127], v[122:123]
	v_rcp_f32_e32 v95, v95
	v_add_f32_e32 v82, v82, v78
	v_add_f32_e32 v83, v83, v79
	v_mul_f32_e32 v82, 0xbfb8aa3b, v82
	v_mul_f32_e32 v83, 0xbfb8aa3b, v83
	v_exp_f32_e32 v82, v82
	v_exp_f32_e32 v83, v83
	v_add_f32_e32 v86, v86, v74
	v_add_f32_e32 v87, v87, v75
	v_add_f32_e32 v82, 1.0, v82
	v_add_f32_e32 v83, 1.0, v83
	v_rcp_f32_e32 v82, v82
	v_rcp_f32_e32 v83, v83
	v_mul_f32_e32 v86, 0xbfb8aa3b, v86
	v_mul_f32_e32 v87, 0xbfb8aa3b, v87
	v_exp_f32_e32 v86, v86
	v_exp_f32_e32 v87, v87
	v_add_f32_e32 v66, v66, v78
	v_add_f32_e32 v67, v67, v79
	v_add_f32_e32 v86, 1.0, v86
	v_add_f32_e32 v87, 1.0, v87
	v_rcp_f32_e32 v86, v86
	v_rcp_f32_e32 v87, v87
	v_mul_f32_e32 v66, 0xbfb8aa3b, v66
	v_mul_f32_e32 v67, 0xbfb8aa3b, v67
	v_exp_f32_e32 v66, v66
	v_exp_f32_e32 v67, v67
	v_add_f32_e32 v70, v70, v74
	v_add_f32_e32 v71, v71, v75
	v_add_f32_e32 v66, 1.0, v66
	v_add_f32_e32 v67, 1.0, v67
	v_rcp_f32_e32 v66, v66
	v_rcp_f32_e32 v67, v67
	v_add_f32_e32 v68, v68, v80
	v_add_f32_e32 v69, v69, v81
	v_mul_f32_e32 v68, 0xbfb8aa3b, v68
	v_pk_mul_f32 v[66:67], v[66:67], v[134:135]
	v_mul_f32_e32 v69, 0xbfb8aa3b, v69
	v_add_f32_e32 v74, v66, v66
	v_add_f32_e32 v75, v67, v67
	v_mul_f32_e32 v74, 0x3fb8aa3b, v74
	v_mul_f32_e32 v75, 0x3fb8aa3b, v75
	v_mul_f32_e32 v70, 0xbfb8aa3b, v70
	v_mul_f32_e32 v71, 0xbfb8aa3b, v71
	v_exp_f32_e32 v74, v74
	v_exp_f32_e32 v75, v75
	v_exp_f32_e32 v68, v68
	v_exp_f32_e32 v69, v69
	v_exp_f32_e32 v70, v70
	v_exp_f32_e32 v71, v71
	v_sub_f32_e32 v74, 1.0, v74
	v_sub_f32_e32 v75, 1.0, v75
	v_add_f32_e32 v68, 1.0, v68
	v_add_f32_e32 v69, 1.0, v69
	v_add_f32_e32 v70, 1.0, v70
	v_add_f32_e32 v71, 1.0, v71
	v_max_f32_e32 v74, 0, v74
	v_max_f32_e32 v75, 0, v75
	v_rcp_f32_e32 v68, v68
	v_rcp_f32_e32 v69, v69
	v_rcp_f32_e32 v70, v70
	s_nop 0
	v_mov_b32_e32 v158, v176
	v_mov_b32_e32 v159, v177
	v_lshlrev_b32_e32 v162, 16, v158
	v_and_b32_e32 v163, 0xffff0000, v158
	v_pk_mul_f32 v[126:127], v[122:123], v[162:163]
	v_add_f32_e32 v123, v128, v76
	v_mul_f32_e32 v123, 0xbfb8aa3b, v123
	v_exp_f32_e32 v123, v123
	v_add_f32_e32 v122, v124, v80
	v_mul_f32_e32 v122, 0xbfb8aa3b, v122
	v_exp_f32_e32 v122, v122
	v_add_f32_e32 v123, 1.0, v123
	v_rcp_f32_e32 v124, v123
	v_add_f32_e32 v123, v125, v81
	v_mul_f32_e32 v123, 0xbfb8aa3b, v123
	v_exp_f32_e32 v123, v123
	v_add_f32_e32 v122, 1.0, v122
	v_rcp_f32_e32 v122, v122
	v_add_f32_e32 v125, v129, v77
	v_add_f32_e32 v123, 1.0, v123
	v_rcp_f32_e32 v123, v123
	v_mul_f32_e32 v125, 0xbfb8aa3b, v125
	v_exp_f32_e32 v125, v125
	v_lshlrev_b32_e32 v158, 16, v159
	v_pk_mul_f32 v[128:129], v[122:123], v[132:133]
	v_and_b32_e32 v159, 0xffff0000, v159
	v_add_f32_e32 v122, v128, v128
	v_add_f32_e32 v123, v129, v129
	v_mul_f32_e32 v122, 0x3fb8aa3b, v122
	v_mul_f32_e32 v123, 0x3fb8aa3b, v123
	v_exp_f32_e32 v122, v122
	v_exp_f32_e32 v123, v123
	v_add_f32_e32 v125, 1.0, v125
	v_rcp_f32_e32 v125, v125
	v_sub_f32_e32 v122, 1.0, v122
	v_sub_f32_e32 v123, 1.0, v123
	v_max_f32_e32 v122, 0, v122
	v_max_f32_e32 v123, 0, v123
	v_sqrt_f32_e32 v122, v122
	v_sqrt_f32_e32 v123, v123
	v_cvt_pk_bf16_f32 v126, v126, v127
	v_rcp_f32_e32 v71, v71
	v_sqrt_f32_e32 v74, v74
	v_pk_mul_f32 v[122:123], v[124:125], v[122:123]
	v_sqrt_f32_e32 v75, v75
	v_pk_mul_f32 v[124:125], v[122:123], v[158:159]
	v_cvt_pk_bf16_f32 v159, v128, v129
	v_mad_i64_i32 v[128:129], s[6:7], v136, s84, v[130:131]
	v_lshl_add_u64 v[128:129], v[128:129], 0, v[146:147]
	v_add_co_u32_e32 v128, vcc, s69, v128
	v_add_u32_e32 v122, 16, v136
	v_cvt_pk_bf16_f32 v158, v160, v161
	v_addc_co_u32_e32 v129, vcc, 0, v129, vcc
	v_cvt_pk_bf16_f32 v127, v124, v125
	v_mov_b32_e32 v160, v158
	v_mov_b32_e32 v161, v159
	v_mov_b32_e32 v164, v126
	v_mov_b32_e32 v165, v127
	v_pk_mul_f32 v[126:127], v[114:115], v[134:135]
	v_ashrrev_i32_e32 v123, 31, v122
	v_lshlrev_b64 v[124:125], 11, v[122:123]
	v_lshl_add_u64 v[124:125], s[14:15], 0, v[124:125]
	v_lshl_add_u64 v[124:125], v[124:125], 0, v[146:147]
	s_nop 0
	v_add_f32_e32 v114, v126, v126
	v_add_f32_e32 v115, v127, v127
	v_mul_f32_e32 v114, 0x3fb8aa3b, v114
	v_mul_f32_e32 v115, 0x3fb8aa3b, v115
	v_exp_f32_e32 v114, v114
	v_exp_f32_e32 v115, v115
	v_pk_mul_f32 v[68:69], v[68:69], v[132:133]
	v_pk_mul_f32 v[70:71], v[70:71], v[74:75]
	v_sub_f32_e32 v114, 1.0, v114
	v_sub_f32_e32 v115, 1.0, v115
	v_max_f32_e32 v114, 0, v114
	v_max_f32_e32 v115, 0, v115
	v_sqrt_f32_e32 v114, v114
	v_sqrt_f32_e32 v115, v115
	v_add_f32_e32 v74, v68, v68
	v_add_f32_e32 v75, v69, v69
	v_add_f32_e32 v72, v72, v76
	v_pk_mul_f32 v[114:115], v[118:119], v[114:115]
	v_add_f32_e32 v73, v73, v77
	v_mul_f32_e32 v74, 0x3fb8aa3b, v74
	v_mul_f32_e32 v75, 0x3fb8aa3b, v75
	v_mul_f32_e32 v72, 0xbfb8aa3b, v72
	v_mul_f32_e32 v73, 0xbfb8aa3b, v73
	v_exp_f32_e32 v74, v74
	v_exp_f32_e32 v75, v75
	v_exp_f32_e32 v72, v72
	v_exp_f32_e32 v73, v73
	v_sub_f32_e32 v74, 1.0, v74
	v_sub_f32_e32 v75, 1.0, v75
	v_add_f32_e32 v72, 1.0, v72
	v_add_f32_e32 v73, 1.0, v73
	v_max_f32_e32 v74, 0, v74
	v_max_f32_e32 v75, 0, v75
	v_rcp_f32_e32 v72, v72
	v_rcp_f32_e32 v73, v73
	v_sqrt_f32_e32 v74, v74
	v_sqrt_f32_e32 v75, v75
	v_cvt_pk_bf16_f32 v66, v66, v67
	v_cvt_pk_bf16_f32 v67, v68, v69
	v_pk_mul_f32 v[72:73], v[72:73], v[74:75]
	v_or_b32_e32 v74, 4, v150
	v_ashrrev_i32_e32 v75, 31, v74
	s_nop 0
	v_mov_b32_e32 v124, v190
	v_mov_b32_e32 v125, v191
	v_lshlrev_b32_e32 v128, 16, v124
	v_and_b32_e32 v129, 0xffff0000, v124
	v_pk_mul_f32 v[118:119], v[114:115], v[128:129]
	v_add_f32_e32 v115, v120, v76
	v_mul_f32_e32 v115, 0xbfb8aa3b, v115
	v_exp_f32_e32 v115, v115
	v_add_f32_e32 v114, v116, v80
	v_mul_f32_e32 v114, 0xbfb8aa3b, v114
	v_exp_f32_e32 v114, v114
	v_add_f32_e32 v115, 1.0, v115
	v_rcp_f32_e32 v116, v115
	v_add_f32_e32 v115, v117, v81
	v_mul_f32_e32 v115, 0xbfb8aa3b, v115
	v_exp_f32_e32 v115, v115
	v_add_f32_e32 v114, 1.0, v114
	v_rcp_f32_e32 v114, v114
	v_add_f32_e32 v117, v121, v77
	v_add_f32_e32 v115, 1.0, v115
	v_rcp_f32_e32 v115, v115
	v_mul_f32_e32 v117, 0xbfb8aa3b, v117
	v_exp_f32_e32 v117, v117
	v_lshlrev_b32_e32 v124, 16, v125
	v_pk_mul_f32 v[120:121], v[114:115], v[132:133]
	v_and_b32_e32 v125, 0xffff0000, v125
	v_add_f32_e32 v114, v120, v120
	v_add_f32_e32 v115, v121, v121
	v_mul_f32_e32 v114, 0x3fb8aa3b, v114
	v_mul_f32_e32 v115, 0x3fb8aa3b, v115
	v_exp_f32_e32 v114, v114
	v_exp_f32_e32 v115, v115
	v_add_f32_e32 v117, 1.0, v117
	v_rcp_f32_e32 v117, v117
	v_sub_f32_e32 v114, 1.0, v114
	v_sub_f32_e32 v115, 1.0, v115
	v_max_f32_e32 v114, 0, v114
	v_max_f32_e32 v115, 0, v115
	v_sqrt_f32_e32 v114, v114
	v_sqrt_f32_e32 v115, v115
	v_cvt_pk_bf16_f32 v118, v118, v119
	v_pk_mul_f32 v[114:115], v[116:117], v[114:115]
	s_nop 0
	v_pk_mul_f32 v[116:117], v[114:115], v[124:125]
	v_cvt_pk_bf16_f32 v125, v120, v121
	v_mad_i64_i32 v[120:121], s[6:7], v122, s84, v[130:131]
	v_lshl_add_u64 v[120:121], v[120:121], 0, v[146:147]
	v_add_co_u32_e32 v120, vcc, s69, v120
	v_add_u32_e32 v114, 16, v122
	v_cvt_pk_bf16_f32 v124, v126, v127
	v_addc_co_u32_e32 v121, vcc, 0, v121, vcc
	v_cvt_pk_bf16_f32 v119, v116, v117
	v_mov_b32_e32 v188, v124
	v_mov_b32_e32 v189, v125
	v_mov_b32_e32 v228, v118
	v_mov_b32_e32 v229, v119
	v_pk_mul_f32 v[118:119], v[106:107], v[134:135]
	v_ashrrev_i32_e32 v115, 31, v114
	v_lshlrev_b64 v[116:117], 11, v[114:115]
	v_lshl_add_u64 v[116:117], s[14:15], 0, v[116:117]
	v_lshl_add_u64 v[116:117], v[116:117], 0, v[146:147]
	s_nop 0
	v_add_f32_e32 v106, v118, v118
	v_add_f32_e32 v107, v119, v119
	v_mul_f32_e32 v106, 0x3fb8aa3b, v106
	v_mul_f32_e32 v107, 0x3fb8aa3b, v107
	v_exp_f32_e32 v106, v106
	v_exp_f32_e32 v107, v107
	v_sub_f32_e32 v106, 1.0, v106
	v_sub_f32_e32 v107, 1.0, v107
	v_max_f32_e32 v106, 0, v106
	v_max_f32_e32 v107, 0, v107
	v_sqrt_f32_e32 v106, v106
	v_sqrt_f32_e32 v107, v107
	s_nop 0
	v_mov_b32_e32 v116, v192
	v_mov_b32_e32 v117, v193
	v_lshlrev_b32_e32 v120, 16, v116
	v_and_b32_e32 v121, 0xffff0000, v116
	v_pk_mul_f32 v[106:107], v[110:111], v[106:107]
	v_lshlrev_b32_e32 v116, 16, v117
	v_pk_mul_f32 v[110:111], v[106:107], v[120:121]
	v_add_f32_e32 v107, v112, v76
	v_mul_f32_e32 v107, 0xbfb8aa3b, v107
	v_exp_f32_e32 v107, v107
	v_add_f32_e32 v106, v108, v80
	v_mul_f32_e32 v106, 0xbfb8aa3b, v106
	v_exp_f32_e32 v106, v106
	v_add_f32_e32 v107, 1.0, v107
	v_rcp_f32_e32 v108, v107
	v_add_f32_e32 v107, v109, v81
	v_mul_f32_e32 v107, 0xbfb8aa3b, v107
	v_exp_f32_e32 v107, v107
	v_add_f32_e32 v106, 1.0, v106
	v_rcp_f32_e32 v106, v106
	v_add_f32_e32 v109, v113, v77
	v_add_f32_e32 v107, 1.0, v107
	v_rcp_f32_e32 v107, v107
	v_mul_f32_e32 v109, 0xbfb8aa3b, v109
	v_exp_f32_e32 v109, v109
	v_and_b32_e32 v117, 0xffff0000, v117
	v_pk_mul_f32 v[112:113], v[106:107], v[132:133]
	v_cvt_pk_bf16_f32 v110, v110, v111
	v_add_f32_e32 v106, v112, v112
	v_add_f32_e32 v107, v113, v113
	v_mul_f32_e32 v106, 0x3fb8aa3b, v106
	v_mul_f32_e32 v107, 0x3fb8aa3b, v107
	v_exp_f32_e32 v106, v106
	v_exp_f32_e32 v107, v107
	v_add_f32_e32 v109, 1.0, v109
	v_rcp_f32_e32 v109, v109
	v_sub_f32_e32 v106, 1.0, v106
	v_sub_f32_e32 v107, 1.0, v107
	v_max_f32_e32 v106, 0, v106
	v_max_f32_e32 v107, 0, v107
	v_sqrt_f32_e32 v106, v106
	v_sqrt_f32_e32 v107, v107
	s_nop 0
	v_pk_mul_f32 v[106:107], v[108:109], v[106:107]
	s_nop 0
	v_pk_mul_f32 v[108:109], v[106:107], v[116:117]
	v_cvt_pk_bf16_f32 v117, v112, v113
	v_mad_i64_i32 v[112:113], s[6:7], v114, s84, v[130:131]
	v_lshl_add_u64 v[112:113], v[112:113], 0, v[146:147]
	v_add_co_u32_e32 v112, vcc, s69, v112
	v_add_u32_e32 v106, 0x50, v114
	v_cvt_pk_bf16_f32 v116, v118, v119
	v_addc_co_u32_e32 v113, vcc, 0, v113, vcc
	v_cvt_pk_bf16_f32 v111, v108, v109
	v_mov_b32_e32 v120, v116
	v_mov_b32_e32 v121, v117
	v_mov_b32_e32 v124, v110
	v_mov_b32_e32 v125, v111
	v_pk_mul_f32 v[110:111], v[98:99], v[134:135]
	v_ashrrev_i32_e32 v107, 31, v106
	v_lshlrev_b64 v[108:109], 11, v[106:107]
	v_lshl_add_u64 v[108:109], s[14:15], 0, v[108:109]
	v_lshl_add_u64 v[108:109], v[108:109], 0, v[146:147]
	s_nop 0
	v_add_f32_e32 v98, v110, v110
	v_add_f32_e32 v99, v111, v111
	v_mul_f32_e32 v98, 0x3fb8aa3b, v98
	v_mul_f32_e32 v99, 0x3fb8aa3b, v99
	v_exp_f32_e32 v98, v98
	v_exp_f32_e32 v99, v99
	v_sub_f32_e32 v98, 1.0, v98
	v_sub_f32_e32 v99, 1.0, v99
	v_max_f32_e32 v98, 0, v98
	v_max_f32_e32 v99, 0, v99
	v_sqrt_f32_e32 v98, v98
	v_sqrt_f32_e32 v99, v99
	s_nop 0
	v_mov_b32_e32 v108, v194
	v_mov_b32_e32 v109, v195
	v_lshlrev_b32_e32 v112, 16, v108
	v_and_b32_e32 v113, 0xffff0000, v108
	v_pk_mul_f32 v[98:99], v[102:103], v[98:99]
	v_lshlrev_b32_e32 v108, 16, v109
	v_pk_mul_f32 v[102:103], v[98:99], v[112:113]
	v_add_f32_e32 v99, v104, v76
	v_mul_f32_e32 v99, 0xbfb8aa3b, v99
	v_exp_f32_e32 v99, v99
	v_add_f32_e32 v98, v100, v80
	v_mul_f32_e32 v98, 0xbfb8aa3b, v98
	v_exp_f32_e32 v98, v98
	v_add_f32_e32 v99, 1.0, v99
	v_rcp_f32_e32 v100, v99
	v_add_f32_e32 v99, v101, v81
	v_mul_f32_e32 v99, 0xbfb8aa3b, v99
	v_exp_f32_e32 v99, v99
	v_add_f32_e32 v98, 1.0, v98
	v_rcp_f32_e32 v98, v98
	v_add_f32_e32 v101, v105, v77
	v_add_f32_e32 v99, 1.0, v99
	v_rcp_f32_e32 v99, v99
	v_mul_f32_e32 v101, 0xbfb8aa3b, v101
	v_exp_f32_e32 v101, v101
	v_and_b32_e32 v109, 0xffff0000, v109
	v_pk_mul_f32 v[104:105], v[98:99], v[132:133]
	v_cvt_pk_bf16_f32 v102, v102, v103
	v_add_f32_e32 v98, v104, v104
	v_add_f32_e32 v99, v105, v105
	v_mul_f32_e32 v98, 0x3fb8aa3b, v98
	v_mul_f32_e32 v99, 0x3fb8aa3b, v99
	v_exp_f32_e32 v98, v98
	v_exp_f32_e32 v99, v99
	v_add_f32_e32 v101, 1.0, v101
	v_rcp_f32_e32 v101, v101
	v_sub_f32_e32 v98, 1.0, v98
	v_sub_f32_e32 v99, 1.0, v99
	v_max_f32_e32 v98, 0, v98
	v_max_f32_e32 v99, 0, v99
	v_sqrt_f32_e32 v98, v98
	v_sqrt_f32_e32 v99, v99
	s_nop 0
	v_pk_mul_f32 v[98:99], v[100:101], v[98:99]
	s_nop 0
	v_pk_mul_f32 v[100:101], v[98:99], v[108:109]
	v_cvt_pk_bf16_f32 v109, v104, v105
	v_mad_i64_i32 v[104:105], s[6:7], v106, s84, v[130:131]
	v_lshl_add_u64 v[104:105], v[104:105], 0, v[146:147]
	v_add_co_u32_e32 v104, vcc, s69, v104
	v_add_u32_e32 v98, 16, v106
	v_cvt_pk_bf16_f32 v108, v110, v111
	v_addc_co_u32_e32 v105, vcc, 0, v105, vcc
	v_cvt_pk_bf16_f32 v103, v100, v101
	v_mov_b32_e32 v112, v108
	v_mov_b32_e32 v113, v109
	v_mov_b32_e32 v116, v102
	v_mov_b32_e32 v117, v103
	v_pk_mul_f32 v[102:103], v[90:91], v[134:135]
	v_ashrrev_i32_e32 v99, 31, v98
	v_lshlrev_b64 v[100:101], 11, v[98:99]
	v_lshl_add_u64 v[100:101], s[14:15], 0, v[100:101]
	v_lshl_add_u64 v[100:101], v[100:101], 0, v[146:147]
	s_nop 0
	v_add_f32_e32 v90, v102, v102
	v_add_f32_e32 v91, v103, v103
	v_mul_f32_e32 v90, 0x3fb8aa3b, v90
	v_mul_f32_e32 v91, 0x3fb8aa3b, v91
	v_exp_f32_e32 v90, v90
	v_exp_f32_e32 v91, v91
	v_sub_f32_e32 v90, 1.0, v90
	v_sub_f32_e32 v91, 1.0, v91
	v_max_f32_e32 v90, 0, v90
	v_max_f32_e32 v91, 0, v91
	v_sqrt_f32_e32 v90, v90
	v_sqrt_f32_e32 v91, v91
	s_nop 0
	v_mov_b32_e32 v100, v196
	v_mov_b32_e32 v101, v197
	v_lshlrev_b32_e32 v104, 16, v100
	v_and_b32_e32 v105, 0xffff0000, v100
	v_pk_mul_f32 v[90:91], v[94:95], v[90:91]
	v_lshlrev_b32_e32 v100, 16, v101
	v_pk_mul_f32 v[94:95], v[90:91], v[104:105]
	v_add_f32_e32 v91, v96, v76
	v_mul_f32_e32 v91, 0xbfb8aa3b, v91
	v_exp_f32_e32 v91, v91
	v_add_f32_e32 v90, v92, v80
	v_mul_f32_e32 v90, 0xbfb8aa3b, v90
	v_exp_f32_e32 v90, v90
	v_add_f32_e32 v91, 1.0, v91
	v_rcp_f32_e32 v92, v91
	v_add_f32_e32 v91, v93, v81
	v_mul_f32_e32 v91, 0xbfb8aa3b, v91
	v_exp_f32_e32 v91, v91
	v_add_f32_e32 v90, 1.0, v90
	v_rcp_f32_e32 v90, v90
	v_add_f32_e32 v93, v97, v77
	v_add_f32_e32 v91, 1.0, v91
	v_rcp_f32_e32 v91, v91
	v_mul_f32_e32 v93, 0xbfb8aa3b, v93
	v_exp_f32_e32 v93, v93
	v_and_b32_e32 v101, 0xffff0000, v101
	v_pk_mul_f32 v[96:97], v[90:91], v[132:133]
	v_cvt_pk_bf16_f32 v94, v94, v95
	v_add_f32_e32 v90, v96, v96
	v_add_f32_e32 v91, v97, v97
	v_mul_f32_e32 v90, 0x3fb8aa3b, v90
	v_mul_f32_e32 v91, 0x3fb8aa3b, v91
	v_exp_f32_e32 v90, v90
	v_exp_f32_e32 v91, v91
	v_add_f32_e32 v93, 1.0, v93
	v_rcp_f32_e32 v93, v93
	v_sub_f32_e32 v90, 1.0, v90
	v_sub_f32_e32 v91, 1.0, v91
	v_max_f32_e32 v90, 0, v90
	v_max_f32_e32 v91, 0, v91
	v_sqrt_f32_e32 v90, v90
	v_sqrt_f32_e32 v91, v91
	s_nop 0
	v_pk_mul_f32 v[90:91], v[92:93], v[90:91]
	s_nop 0
	v_pk_mul_f32 v[92:93], v[90:91], v[100:101]
	v_cvt_pk_bf16_f32 v101, v96, v97
	v_mad_i64_i32 v[96:97], s[6:7], v98, s84, v[130:131]
	v_lshl_add_u64 v[96:97], v[96:97], 0, v[146:147]
	v_add_co_u32_e32 v96, vcc, s69, v96
	v_add_u32_e32 v90, 16, v98
	v_cvt_pk_bf16_f32 v100, v102, v103
	v_addc_co_u32_e32 v97, vcc, 0, v97, vcc
	v_cvt_pk_bf16_f32 v95, v92, v93
	v_mov_b32_e32 v104, v100
	v_mov_b32_e32 v105, v101
	v_mov_b32_e32 v108, v94
	v_mov_b32_e32 v109, v95
	v_pk_mul_f32 v[94:95], v[82:83], v[134:135]
	v_ashrrev_i32_e32 v91, 31, v90
	v_lshlrev_b64 v[92:93], 11, v[90:91]
	v_lshl_add_u64 v[92:93], s[14:15], 0, v[92:93]
	v_lshl_add_u64 v[92:93], v[92:93], 0, v[146:147]
	s_nop 0
	v_add_f32_e32 v82, v94, v94
	v_add_f32_e32 v83, v95, v95
	v_mul_f32_e32 v82, 0x3fb8aa3b, v82
	v_mul_f32_e32 v83, 0x3fb8aa3b, v83
	v_exp_f32_e32 v82, v82
	v_exp_f32_e32 v83, v83
	v_sub_f32_e32 v82, 1.0, v82
	v_sub_f32_e32 v83, 1.0, v83
	v_max_f32_e32 v82, 0, v82
	v_max_f32_e32 v83, 0, v83
	v_sqrt_f32_e32 v82, v82
	v_sqrt_f32_e32 v83, v83
	s_nop 0
	v_mov_b32_e32 v92, v198
	v_mov_b32_e32 v93, v199
	v_lshlrev_b32_e32 v96, 16, v92
	v_and_b32_e32 v97, 0xffff0000, v92
	v_pk_mul_f32 v[82:83], v[86:87], v[82:83]
	v_lshlrev_b32_e32 v92, 16, v93
	v_pk_mul_f32 v[86:87], v[82:83], v[96:97]
	v_add_f32_e32 v83, v88, v76
	v_mul_f32_e32 v83, 0xbfb8aa3b, v83
	v_exp_f32_e32 v83, v83
	v_add_f32_e32 v82, v84, v80
	v_mul_f32_e32 v82, 0xbfb8aa3b, v82
	v_exp_f32_e32 v82, v82
	v_add_f32_e32 v83, 1.0, v83
	v_rcp_f32_e32 v84, v83
	v_add_f32_e32 v83, v85, v81
	v_mul_f32_e32 v83, 0xbfb8aa3b, v83
	v_exp_f32_e32 v83, v83
	v_add_f32_e32 v82, 1.0, v82
	v_rcp_f32_e32 v82, v82
	v_add_f32_e32 v85, v89, v77
	v_add_f32_e32 v83, 1.0, v83
	v_rcp_f32_e32 v83, v83
	v_mul_f32_e32 v85, 0xbfb8aa3b, v85
	v_exp_f32_e32 v85, v85
	v_and_b32_e32 v93, 0xffff0000, v93
	v_pk_mul_f32 v[88:89], v[82:83], v[132:133]
	v_cvt_pk_bf16_f32 v86, v86, v87
	v_add_f32_e32 v82, v88, v88
	v_add_f32_e32 v83, v89, v89
	v_mul_f32_e32 v82, 0x3fb8aa3b, v82
	v_mul_f32_e32 v83, 0x3fb8aa3b, v83
	v_exp_f32_e32 v82, v82
	v_exp_f32_e32 v83, v83
	v_add_f32_e32 v85, 1.0, v85
	v_rcp_f32_e32 v85, v85
	v_sub_f32_e32 v82, 1.0, v82
	v_sub_f32_e32 v83, 1.0, v83
	v_max_f32_e32 v82, 0, v82
	v_max_f32_e32 v83, 0, v83
	v_sqrt_f32_e32 v82, v82
	v_sqrt_f32_e32 v83, v83
	s_nop 0
	v_pk_mul_f32 v[82:83], v[84:85], v[82:83]
	s_nop 0
	v_pk_mul_f32 v[84:85], v[82:83], v[92:93]
	v_cvt_pk_bf16_f32 v93, v88, v89
	v_mad_i64_i32 v[88:89], s[6:7], v90, s84, v[130:131]
	v_lshl_add_u64 v[88:89], v[88:89], 0, v[146:147]
	v_add_co_u32_e32 v88, vcc, s69, v88
	v_add_u32_e32 v82, 16, v90
	v_cvt_pk_bf16_f32 v92, v94, v95
	v_addc_co_u32_e32 v89, vcc, 0, v89, vcc
	v_cvt_pk_bf16_f32 v87, v84, v85
	v_mov_b32_e32 v96, v92
	v_mov_b32_e32 v97, v93
	v_mov_b32_e32 v100, v86
	v_mov_b32_e32 v101, v87
	s_nop 0
	v_ashrrev_i32_e32 v83, 31, v82
	v_lshlrev_b64 v[84:85], 11, v[82:83]
	v_lshl_add_u64 v[84:85], s[14:15], 0, v[84:85]
	v_lshl_add_u64 v[84:85], v[84:85], 0, v[146:147]
	s_nop 0
	v_mad_i64_i32 v[68:69], s[6:7], v82, s84, v[130:131]
	v_lshl_add_u64 v[68:69], v[68:69], 0, v[146:147]
	v_add_co_u32_e32 v68, vcc, s69, v68
	s_nop 0
	v_mov_b32_e32 v84, v200
	v_mov_b32_e32 v85, v201
	v_lshlrev_b32_e32 v78, 16, v84
	v_and_b32_e32 v79, 0xffff0000, v84
	v_lshlrev_b32_e32 v76, 16, v85
	v_and_b32_e32 v77, 0xffff0000, v85
	v_pk_mul_f32 v[70:71], v[70:71], v[78:79]
	v_pk_mul_f32 v[72:73], v[72:73], v[76:77]
	v_addc_co_u32_e32 v69, vcc, 0, v69, vcc
	v_mov_b32_e32 v88, v66
	v_mov_b32_e32 v89, v67
	v_cvt_pk_bf16_f32 v66, v70, v71
	v_cvt_pk_bf16_f32 v67, v72, v73
	v_mov_b32_e32 v92, v66
	v_mov_b32_e32 v93, v67
	global_load_dwordx4 v[70:73], v[152:153], off offset:16
	s_nop 0
	global_load_dwordx4 v[66:69], v[156:157], off offset:16
	global_load_dwordx4 v[76:79], v[154:155], off offset:16
	s_waitcnt vmcnt(0)
	v_add_f32_e32 v58, v58, v70
	v_ashrrev_i32_e32 v149, 31, v148
	v_max_f32_e64 v80, -v76, -v76
	v_mul_f32_e64 v76, |v76|, s72
	v_exp_f32_e32 v76, v76
	v_mul_f32_e32 v58, 0xbfb8aa3b, v58
	v_exp_f32_e32 v58, v58
	v_max_f32_e32 v80, 0, v80
	v_add_f32_e32 v76, 1.0, v76
	v_cmp_gt_f32_e32 vcc, s71, v76
	v_add_f32_e32 v58, 1.0, v58
	v_rcp_f32_e32 v86, v58
	v_cndmask_b32_e64 v81, 0, 32, vcc
	v_ldexp_f32 v76, v76, v81
	v_log_f32_e32 v76, v76
	v_add_f32_e32 v58, v62, v66
	v_mul_f32_e32 v58, 0xbfb8aa3b, v58
	v_exp_f32_e32 v58, v58
	v_mul_f32_e32 v81, 0x3f317217, v76
	v_fma_f32 v81, v76, s73, -v81
	v_fmac_f32_e32 v81, 0x3377d1cf, v76
	v_fmac_f32_e32 v81, 0x3f317217, v76
	v_cmp_lt_f32_e64 s[6:7], |v76|, s74
	v_add_f32_e32 v58, 1.0, v58
	v_rcp_f32_e32 v62, v58
	v_cndmask_b32_e64 v76, v76, v81, s[6:7]
	v_cndmask_b32_e32 v81, 0, v243, vcc
	v_sub_f32_e32 v82, v76, v81
	v_max_f32_e64 v76, -v77, -v77
	v_max_f32_e32 v81, 0, v76
	v_mul_f32_e64 v76, |v77|, s72
	v_exp_f32_e32 v76, v76
	v_add_f32_e32 v58, v59, v71
	v_mul_f32_e32 v58, 0xbfb8aa3b, v58
	v_exp_f32_e32 v58, v58
	v_add_f32_e32 v76, 1.0, v76
	v_cmp_gt_f32_e32 vcc, s71, v76
	v_add_f32_e32 v60, v60, v72
	v_add_f32_e32 v58, 1.0, v58
	v_cndmask_b32_e64 v77, 0, 32, vcc
	v_ldexp_f32 v76, v76, v77
	v_log_f32_e32 v76, v76
	v_rcp_f32_e32 v87, v58
	v_add_f32_e32 v58, v63, v67
	v_mul_f32_e32 v58, 0xbfb8aa3b, v58
	v_mul_f32_e32 v77, 0x3f317217, v76
	v_fma_f32 v77, v76, s73, -v77
	v_fmac_f32_e32 v77, 0x3377d1cf, v76
	v_fmac_f32_e32 v77, 0x3f317217, v76
	v_cmp_lt_f32_e64 s[6:7], |v76|, s74
	v_exp_f32_e32 v58, v58
	v_mul_f32_e32 v60, 0xbfb8aa3b, v60
	v_cndmask_b32_e64 v76, v76, v77, s[6:7]
	v_cndmask_b32_e32 v77, 0, v243, vcc
	v_sub_f32_e32 v83, v76, v77
	v_mul_f32_e64 v77, |v78|, s72
	v_exp_f32_e32 v77, v77
	v_max_f32_e64 v76, -v78, -v78
	v_add_f32_e32 v58, 1.0, v58
	v_rcp_f32_e32 v63, v58
	v_add_f32_e32 v77, 1.0, v77
	v_cmp_gt_f32_e32 vcc, s71, v77
	v_pk_add_f32 v[58:59], v[80:81], v[82:83]
	v_exp_f32_e32 v60, v60
	v_cndmask_b32_e64 v78, 0, 32, vcc
	v_ldexp_f32 v77, v77, v78
	v_log_f32_e32 v77, v77
	v_pk_mul_f32 v[58:59], v[58:59], s[2:3] op_sel_hi:[1,0]
	v_add_f32_e32 v60, 1.0, v60
	v_pk_mul_f32 v[80:81], v[86:87], v[58:59]
	v_mul_f32_e32 v78, 0x3f317217, v77
	v_fma_f32 v78, v77, s73, -v78
	v_fmac_f32_e32 v78, 0x3377d1cf, v77
	v_fmac_f32_e32 v78, 0x3f317217, v77
	v_cmp_lt_f32_e64 s[6:7], |v77|, s74
	v_add_f32_e32 v82, v80, v80
	v_add_f32_e32 v83, v81, v81
	v_cndmask_b32_e64 v77, v77, v78, s[6:7]
	v_cndmask_b32_e32 v78, 0, v243, vcc
	v_sub_f32_e32 v78, v77, v78
	v_max_f32_e64 v77, -v79, -v79
	v_mul_f32_e64 v79, |v79|, s72
	v_exp_f32_e32 v79, v79
	v_mul_f32_e32 v82, 0x3fb8aa3b, v82
	v_mul_f32_e32 v83, 0x3fb8aa3b, v83
	v_exp_f32_e32 v82, v82
	v_add_f32_e32 v79, 1.0, v79
	v_cmp_gt_f32_e32 vcc, s71, v79
	v_exp_f32_e32 v83, v83
	v_sub_f32_e32 v82, 1.0, v82
	v_cndmask_b32_e64 v84, 0, 32, vcc
	v_ldexp_f32 v79, v79, v84
	v_log_f32_e32 v79, v79
	v_sub_f32_e32 v83, 1.0, v83
	v_max_f32_e32 v82, 0, v82
	v_max_f32_e32 v83, 0, v83
	v_mul_f32_e32 v84, 0x3f317217, v79
	v_fma_f32 v84, v79, s73, -v84
	v_fmac_f32_e32 v84, 0x3377d1cf, v79
	v_fmac_f32_e32 v84, 0x3f317217, v79
	v_cmp_lt_f32_e64 s[6:7], |v79|, s74
	v_sqrt_f32_e32 v82, v82
	v_sqrt_f32_e32 v83, v83
	v_cndmask_b32_e64 v79, v79, v84, s[6:7]
	v_cndmask_b32_e32 v84, 0, v243, vcc
	v_sub_f32_e32 v79, v79, v84
	v_lshlrev_b64 v[84:85], 11, v[148:149]
	v_lshl_add_u64 v[84:85], s[14:15], 0, v[84:85]
	v_lshl_add_u64 v[84:85], v[84:85], 0, v[146:147]
	s_nop 0
	v_pk_mul_f32 v[62:63], v[62:63], v[82:83]
	v_max_f32_e32 v76, 0, v76
	v_max_f32_e32 v77, 0, v77
	v_add_f32_e32 v50, v50, v70
	v_add_f32_e32 v51, v51, v71
	v_mul_f32_e32 v50, 0xbfb8aa3b, v50
	v_mul_f32_e32 v51, 0xbfb8aa3b, v51
	v_exp_f32_e32 v50, v50
	v_exp_f32_e32 v51, v51
	v_add_f32_e32 v54, v54, v66
	v_add_f32_e32 v55, v55, v67
	v_add_f32_e32 v50, 1.0, v50
	v_add_f32_e32 v51, 1.0, v51
	v_rcp_f32_e32 v50, v50
	v_rcp_f32_e32 v51, v51
	v_mul_f32_e32 v54, 0xbfb8aa3b, v54
	v_mul_f32_e32 v55, 0xbfb8aa3b, v55
	v_exp_f32_e32 v54, v54
	v_exp_f32_e32 v55, v55
	v_add_f32_e32 v42, v42, v70
	v_add_f32_e32 v43, v43, v71
	v_add_f32_e32 v54, 1.0, v54
	v_add_f32_e32 v55, 1.0, v55
	v_rcp_f32_e32 v54, v54
	v_rcp_f32_e32 v55, v55
	v_mul_f32_e32 v42, 0xbfb8aa3b, v42
	v_mul_f32_e32 v43, 0xbfb8aa3b, v43
	v_exp_f32_e32 v42, v42
	v_exp_f32_e32 v43, v43
	v_add_f32_e32 v46, v46, v66
	v_add_f32_e32 v47, v47, v67
	v_add_f32_e32 v42, 1.0, v42
	v_add_f32_e32 v43, 1.0, v43
	v_rcp_f32_e32 v42, v42
	v_rcp_f32_e32 v43, v43
	v_mul_f32_e32 v46, 0xbfb8aa3b, v46
	v_mul_f32_e32 v47, 0xbfb8aa3b, v47
	v_exp_f32_e32 v46, v46
	v_exp_f32_e32 v47, v47
	v_add_f32_e32 v34, v34, v70
	v_add_f32_e32 v35, v35, v71
	v_add_f32_e32 v46, 1.0, v46
	v_add_f32_e32 v47, 1.0, v47
	v_rcp_f32_e32 v46, v46
	v_rcp_f32_e32 v47, v47
	v_mul_f32_e32 v34, 0xbfb8aa3b, v34
	v_mul_f32_e32 v35, 0xbfb8aa3b, v35
	v_exp_f32_e32 v34, v34
	v_exp_f32_e32 v35, v35
	v_add_f32_e32 v38, v38, v66
	v_add_f32_e32 v39, v39, v67
	v_add_f32_e32 v34, 1.0, v34
	v_add_f32_e32 v35, 1.0, v35
	v_rcp_f32_e32 v34, v34
	v_rcp_f32_e32 v35, v35
	v_mul_f32_e32 v38, 0xbfb8aa3b, v38
	v_mul_f32_e32 v39, 0xbfb8aa3b, v39
	v_exp_f32_e32 v38, v38
	v_exp_f32_e32 v39, v39
	v_add_f32_e32 v26, v26, v70
	v_add_f32_e32 v27, v27, v71
	v_add_f32_e32 v38, 1.0, v38
	v_add_f32_e32 v39, 1.0, v39
	v_rcp_f32_e32 v38, v38
	v_rcp_f32_e32 v39, v39
	v_mul_f32_e32 v26, 0xbfb8aa3b, v26
	v_mul_f32_e32 v27, 0xbfb8aa3b, v27
	v_exp_f32_e32 v26, v26
	v_exp_f32_e32 v27, v27
	v_add_f32_e32 v30, v30, v66
	v_add_f32_e32 v31, v31, v67
	v_add_f32_e32 v26, 1.0, v26
	v_add_f32_e32 v27, 1.0, v27
	v_rcp_f32_e32 v26, v26
	v_rcp_f32_e32 v27, v27
	v_mul_f32_e32 v30, 0xbfb8aa3b, v30
	v_mul_f32_e32 v31, 0xbfb8aa3b, v31
	v_exp_f32_e32 v30, v30
	v_exp_f32_e32 v31, v31
	s_nop 0
	v_mov_b32_e32 v84, v202
	v_mov_b32_e32 v85, v203
	v_lshlrev_b32_e32 v86, 16, v84
	v_and_b32_e32 v87, 0xffff0000, v84
	v_pk_mul_f32 v[82:83], v[62:63], v[86:87]
	v_rcp_f32_e32 v62, v60
	v_add_f32_e32 v60, v64, v68
	v_mul_f32_e32 v60, 0xbfb8aa3b, v60
	v_exp_f32_e32 v60, v60
	v_add_f32_e32 v30, 1.0, v30
	v_add_f32_e32 v31, 1.0, v31
	v_rcp_f32_e32 v30, v30
	v_add_f32_e32 v60, 1.0, v60
	v_rcp_f32_e32 v64, v60
	v_add_f32_e32 v60, v61, v73
	v_mul_f32_e32 v60, 0xbfb8aa3b, v60
	v_exp_f32_e32 v60, v60
	v_rcp_f32_e32 v31, v31
	v_add_f32_e32 v18, v18, v70
	v_add_f32_e32 v19, v19, v71
	v_add_f32_e32 v60, 1.0, v60
	v_rcp_f32_e32 v63, v60
	v_add_f32_e32 v60, v65, v69
	v_mul_f32_e32 v60, 0xbfb8aa3b, v60
	v_exp_f32_e32 v60, v60
	v_mul_f32_e32 v18, 0xbfb8aa3b, v18
	v_mul_f32_e32 v19, 0xbfb8aa3b, v19
	v_exp_f32_e32 v18, v18
	v_add_f32_e32 v60, 1.0, v60
	v_rcp_f32_e32 v65, v60
	v_pk_add_f32 v[60:61], v[76:77], v[78:79]
	v_lshlrev_b32_e32 v78, 16, v85
	v_pk_mul_f32 v[60:61], v[60:61], s[2:3] op_sel_hi:[1,0]
	v_and_b32_e32 v79, 0xffff0000, v85
	v_pk_mul_f32 v[62:63], v[62:63], v[60:61]
	v_exp_f32_e32 v19, v19
	v_add_f32_e32 v76, v62, v62
	v_add_f32_e32 v77, v63, v63
	v_mul_f32_e32 v76, 0x3fb8aa3b, v76
	v_mul_f32_e32 v77, 0x3fb8aa3b, v77
	v_exp_f32_e32 v76, v76
	v_exp_f32_e32 v77, v77
	v_add_f32_e32 v18, 1.0, v18
	v_add_f32_e32 v19, 1.0, v19
	v_sub_f32_e32 v76, 1.0, v76
	v_sub_f32_e32 v77, 1.0, v77
	v_max_f32_e32 v76, 0, v76
	v_max_f32_e32 v77, 0, v77
	v_sqrt_f32_e32 v76, v76
	v_sqrt_f32_e32 v77, v77
	v_rcp_f32_e32 v18, v18
	v_rcp_f32_e32 v19, v19
	v_add_f32_e32 v22, v22, v66
	v_pk_mul_f32 v[64:65], v[64:65], v[76:77]
	v_add_f32_e32 v23, v23, v67
	v_pk_mul_f32 v[76:77], v[64:65], v[78:79]
	v_cvt_pk_bf16_f32 v78, v80, v81
	v_cvt_pk_bf16_f32 v79, v62, v63
	v_mad_i64_i32 v[80:81], s[6:7], v148, s84, v[130:131]
	v_lshlrev_b64 v[62:63], 1, v[74:75]
	v_lshl_add_u64 v[74:75], v[80:81], 0, v[62:63]
	v_add_co_u32_e32 v74, vcc, s69, v74
	v_add_u32_e32 v64, 16, v148
	s_nop 0
	v_addc_co_u32_e32 v75, vcc, 0, v75, vcc
	v_mov_b32_e32 v222, v78
	v_mov_b32_e32 v223, v79
	global_store_dwordx4 v[74:75], v[220:223], off offset:2040
	v_cvt_pk_bf16_f32 v78, v82, v83
	v_cvt_pk_bf16_f32 v79, v76, v77
	v_mov_b32_e32 v226, v78
	v_mov_b32_e32 v227, v79
	global_store_dwordx4 v[74:75], v[224:227], off offset:-8
	v_pk_mul_f32 v[76:77], v[50:51], v[58:59]
	v_ashrrev_i32_e32 v65, 31, v64
	v_lshlrev_b64 v[74:75], 11, v[64:65]
	v_lshl_add_u64 v[74:75], s[14:15], 0, v[74:75]
	v_lshl_add_u64 v[74:75], v[74:75], 0, v[146:147]
	s_nop 0
	v_add_f32_e32 v50, v76, v76
	v_add_f32_e32 v51, v77, v77
	v_mul_f32_e32 v50, 0x3fb8aa3b, v50
	v_mul_f32_e32 v51, 0x3fb8aa3b, v51
	v_exp_f32_e32 v50, v50
	v_exp_f32_e32 v51, v51
	v_mul_f32_e32 v22, 0xbfb8aa3b, v22
	v_mul_f32_e32 v23, 0xbfb8aa3b, v23
	v_sub_f32_e32 v50, 1.0, v50
	v_sub_f32_e32 v51, 1.0, v51
	v_max_f32_e32 v50, 0, v50
	v_max_f32_e32 v51, 0, v51
	v_sqrt_f32_e32 v50, v50
	v_sqrt_f32_e32 v51, v51
	v_exp_f32_e32 v22, v22
	v_exp_f32_e32 v23, v23
	v_add_f32_e32 v10, v10, v70
	v_pk_mul_f32 v[50:51], v[54:55], v[50:51]
	v_add_f32_e32 v22, 1.0, v22
	v_add_f32_e32 v23, 1.0, v23
	v_rcp_f32_e32 v22, v22
	v_rcp_f32_e32 v23, v23
	v_add_f32_e32 v11, v11, v71
	v_mul_f32_e32 v10, 0xbfb8aa3b, v10
	v_mul_f32_e32 v11, 0xbfb8aa3b, v11
	v_exp_f32_e32 v10, v10
	v_exp_f32_e32 v11, v11
	v_add_f32_e32 v14, v14, v66
	v_add_f32_e32 v15, v15, v67
	v_add_f32_e32 v10, 1.0, v10
	v_add_f32_e32 v11, 1.0, v11
	v_rcp_f32_e32 v10, v10
	v_rcp_f32_e32 v11, v11
	v_mul_f32_e32 v14, 0xbfb8aa3b, v14
	v_mul_f32_e32 v15, 0xbfb8aa3b, v15
	v_exp_f32_e32 v14, v14
	v_exp_f32_e32 v15, v15
	v_add_f32_e32 v2, v2, v70
	v_add_f32_e32 v3, v3, v71
	v_add_f32_e32 v14, 1.0, v14
	v_add_f32_e32 v15, 1.0, v15
	v_rcp_f32_e32 v14, v14
	v_rcp_f32_e32 v15, v15
	v_mul_f32_e32 v2, 0xbfb8aa3b, v2
	v_mul_f32_e32 v3, 0xbfb8aa3b, v3
	v_exp_f32_e32 v2, v2
	v_exp_f32_e32 v3, v3
	v_add_f32_e32 v4, v4, v72
	v_add_f32_e32 v5, v5, v73
	v_add_f32_e32 v2, 1.0, v2
	v_add_f32_e32 v3, 1.0, v3
	v_rcp_f32_e32 v2, v2
	v_rcp_f32_e32 v3, v3
	v_mul_f32_e32 v4, 0xbfb8aa3b, v4
	v_mul_f32_e32 v5, 0xbfb8aa3b, v5
	v_exp_f32_e32 v4, v4
	v_pk_mul_f32 v[2:3], v[2:3], v[58:59]
	v_exp_f32_e32 v5, v5
	v_add_f32_e32 v6, v6, v66
	v_add_f32_e32 v4, 1.0, v4
	v_rcp_f32_e32 v4, v4
	v_add_f32_e32 v5, 1.0, v5
	v_rcp_f32_e32 v5, v5
	v_add_f32_e32 v7, v7, v67
	v_mul_f32_e32 v6, 0xbfb8aa3b, v6
	v_mul_f32_e32 v7, 0xbfb8aa3b, v7
	v_exp_f32_e32 v6, v6
	v_exp_f32_e32 v7, v7
	v_pk_mul_f32 v[4:5], v[4:5], v[60:61]
	v_add_f32_e32 v8, v8, v68
	v_add_f32_e32 v6, 1.0, v6
	v_add_f32_e32 v7, 1.0, v7
	v_rcp_f32_e32 v6, v6
	v_rcp_f32_e32 v7, v7
	v_add_f32_e32 v9, v9, v69
	v_mul_f32_e32 v8, 0xbfb8aa3b, v8
	v_mul_f32_e32 v9, 0xbfb8aa3b, v9
	v_exp_f32_e32 v8, v8
	v_exp_f32_e32 v9, v9
	s_nop 0
	v_mov_b32_e32 v74, v204
	v_mov_b32_e32 v75, v205
	v_lshlrev_b32_e32 v78, 16, v74
	v_and_b32_e32 v79, 0xffff0000, v74
	v_pk_mul_f32 v[54:55], v[50:51], v[78:79]
	v_add_f32_e32 v51, v56, v68
	v_mul_f32_e32 v51, 0xbfb8aa3b, v51
	v_exp_f32_e32 v51, v51
	v_add_f32_e32 v50, v52, v72
	v_mul_f32_e32 v50, 0xbfb8aa3b, v50
	v_exp_f32_e32 v50, v50
	v_add_f32_e32 v51, 1.0, v51
	v_rcp_f32_e32 v52, v51
	v_add_f32_e32 v51, v53, v73
	v_mul_f32_e32 v51, 0xbfb8aa3b, v51
	v_exp_f32_e32 v51, v51
	v_add_f32_e32 v50, 1.0, v50
	v_rcp_f32_e32 v50, v50
	v_add_f32_e32 v53, v57, v69
	v_add_f32_e32 v51, 1.0, v51
	v_rcp_f32_e32 v51, v51
	v_mul_f32_e32 v53, 0xbfb8aa3b, v53
	v_exp_f32_e32 v53, v53
	v_lshlrev_b32_e32 v74, 16, v75
	v_pk_mul_f32 v[56:57], v[50:51], v[60:61]
	v_and_b32_e32 v75, 0xffff0000, v75
	v_add_f32_e32 v50, v56, v56
	v_add_f32_e32 v51, v57, v57
	v_mul_f32_e32 v50, 0x3fb8aa3b, v50
	v_mul_f32_e32 v51, 0x3fb8aa3b, v51
	v_exp_f32_e32 v50, v50
	v_exp_f32_e32 v51, v51
	v_add_f32_e32 v53, 1.0, v53
	v_rcp_f32_e32 v53, v53
	v_sub_f32_e32 v50, 1.0, v50
	v_sub_f32_e32 v51, 1.0, v51
	v_max_f32_e32 v50, 0, v50
	v_max_f32_e32 v51, 0, v51
	v_sqrt_f32_e32 v50, v50
	v_sqrt_f32_e32 v51, v51
	v_cvt_pk_bf16_f32 v54, v54, v55
	v_add_f32_e32 v8, 1.0, v8
	v_add_f32_e32 v9, 1.0, v9
	v_pk_mul_f32 v[50:51], v[52:53], v[50:51]
	v_rcp_f32_e32 v8, v8
	v_pk_mul_f32 v[52:53], v[50:51], v[74:75]
	v_cvt_pk_bf16_f32 v75, v56, v57
	v_mad_i64_i32 v[56:57], s[6:7], v64, s84, v[130:131]
	v_lshl_add_u64 v[56:57], v[56:57], 0, v[62:63]
	v_add_co_u32_e32 v56, vcc, s69, v56
	v_add_u32_e32 v50, 16, v64
	v_cvt_pk_bf16_f32 v74, v76, v77
	v_addc_co_u32_e32 v57, vcc, 0, v57, vcc
	v_cvt_pk_bf16_f32 v55, v52, v53
	v_mov_b32_e32 v162, v74
	v_mov_b32_e32 v163, v75
	global_store_dwordx4 v[56:57], v[160:163], off offset:2040
	v_mov_b32_e32 v166, v54
	v_mov_b32_e32 v167, v55
	global_store_dwordx4 v[56:57], v[164:167], off offset:-8
	v_pk_mul_f32 v[54:55], v[42:43], v[58:59]
	v_ashrrev_i32_e32 v51, 31, v50
	v_lshlrev_b64 v[52:53], 11, v[50:51]
	v_lshl_add_u64 v[52:53], s[14:15], 0, v[52:53]
	v_lshl_add_u64 v[52:53], v[52:53], 0, v[146:147]
	s_nop 0
	v_add_f32_e32 v42, v54, v54
	v_add_f32_e32 v43, v55, v55
	v_mul_f32_e32 v42, 0x3fb8aa3b, v42
	v_mul_f32_e32 v43, 0x3fb8aa3b, v43
	v_exp_f32_e32 v42, v42
	v_exp_f32_e32 v43, v43
	v_rcp_f32_e32 v9, v9
	s_mov_b32 s2, s22
	v_sub_f32_e32 v42, 1.0, v42
	v_sub_f32_e32 v43, 1.0, v43
	v_max_f32_e32 v42, 0, v42
	v_max_f32_e32 v43, 0, v43
	v_sqrt_f32_e32 v42, v42
	v_sqrt_f32_e32 v43, v43
	s_nop 0
	v_mov_b32_e32 v52, v206
	v_mov_b32_e32 v53, v207
	v_lshlrev_b32_e32 v56, 16, v52
	v_and_b32_e32 v57, 0xffff0000, v52
	v_pk_mul_f32 v[42:43], v[46:47], v[42:43]
	v_lshlrev_b32_e32 v52, 16, v53
	v_pk_mul_f32 v[46:47], v[42:43], v[56:57]
	v_add_f32_e32 v43, v48, v68
	v_mul_f32_e32 v43, 0xbfb8aa3b, v43
	v_exp_f32_e32 v43, v43
	v_add_f32_e32 v42, v44, v72
	v_mul_f32_e32 v42, 0xbfb8aa3b, v42
	v_exp_f32_e32 v42, v42
	v_add_f32_e32 v43, 1.0, v43
	v_rcp_f32_e32 v44, v43
	v_add_f32_e32 v43, v45, v73
	v_mul_f32_e32 v43, 0xbfb8aa3b, v43
	v_exp_f32_e32 v43, v43
	v_add_f32_e32 v42, 1.0, v42
	v_rcp_f32_e32 v42, v42
	v_add_f32_e32 v45, v49, v69
	v_add_f32_e32 v43, 1.0, v43
	v_rcp_f32_e32 v43, v43
	v_mul_f32_e32 v45, 0xbfb8aa3b, v45
	v_exp_f32_e32 v45, v45
	v_and_b32_e32 v53, 0xffff0000, v53
	v_pk_mul_f32 v[48:49], v[42:43], v[60:61]
	v_cvt_pk_bf16_f32 v46, v46, v47
	v_add_f32_e32 v42, v48, v48
	v_add_f32_e32 v43, v49, v49
	v_mul_f32_e32 v42, 0x3fb8aa3b, v42
	v_mul_f32_e32 v43, 0x3fb8aa3b, v43
	v_exp_f32_e32 v42, v42
	v_exp_f32_e32 v43, v43
	v_add_f32_e32 v45, 1.0, v45
	v_rcp_f32_e32 v45, v45
	v_sub_f32_e32 v42, 1.0, v42
	v_sub_f32_e32 v43, 1.0, v43
	v_max_f32_e32 v42, 0, v42
	v_max_f32_e32 v43, 0, v43
	v_sqrt_f32_e32 v42, v42
	v_sqrt_f32_e32 v43, v43
	s_nop 0
	v_pk_mul_f32 v[42:43], v[44:45], v[42:43]
	s_nop 0
	v_pk_mul_f32 v[44:45], v[42:43], v[52:53]
	v_cvt_pk_bf16_f32 v53, v48, v49
	v_mad_i64_i32 v[48:49], s[6:7], v50, s84, v[130:131]
	v_lshl_add_u64 v[48:49], v[48:49], 0, v[62:63]
	v_add_co_u32_e32 v48, vcc, s69, v48
	v_add_u32_e32 v42, 16, v50
	v_cvt_pk_bf16_f32 v52, v54, v55
	v_addc_co_u32_e32 v49, vcc, 0, v49, vcc
	v_cvt_pk_bf16_f32 v47, v44, v45
	v_mov_b32_e32 v190, v52
	v_mov_b32_e32 v191, v53
	global_store_dwordx4 v[48:49], v[188:191], off offset:2040
	v_mov_b32_e32 v230, v46
	v_mov_b32_e32 v231, v47
	global_store_dwordx4 v[48:49], v[228:231], off offset:-8
	v_pk_mul_f32 v[46:47], v[34:35], v[58:59]
	v_ashrrev_i32_e32 v43, 31, v42
	v_lshlrev_b64 v[44:45], 11, v[42:43]
	v_lshl_add_u64 v[44:45], s[14:15], 0, v[44:45]
	v_lshl_add_u64 v[44:45], v[44:45], 0, v[146:147]
	s_nop 0
	v_add_f32_e32 v34, v46, v46
	v_add_f32_e32 v35, v47, v47
	v_mul_f32_e32 v34, 0x3fb8aa3b, v34
	v_mul_f32_e32 v35, 0x3fb8aa3b, v35
	v_exp_f32_e32 v34, v34
	v_exp_f32_e32 v35, v35
	v_sub_f32_e32 v34, 1.0, v34
	v_sub_f32_e32 v35, 1.0, v35
	v_max_f32_e32 v34, 0, v34
	v_max_f32_e32 v35, 0, v35
	v_sqrt_f32_e32 v34, v34
	v_sqrt_f32_e32 v35, v35
	s_nop 0
	v_mov_b32_e32 v44, v208
	v_mov_b32_e32 v45, v209
	v_lshlrev_b32_e32 v48, 16, v44
	v_and_b32_e32 v49, 0xffff0000, v44
	v_pk_mul_f32 v[34:35], v[38:39], v[34:35]
	v_lshlrev_b32_e32 v44, 16, v45
	v_pk_mul_f32 v[38:39], v[34:35], v[48:49]
	v_add_f32_e32 v35, v40, v68
	v_mul_f32_e32 v35, 0xbfb8aa3b, v35
	v_exp_f32_e32 v35, v35
	v_add_f32_e32 v34, v36, v72
	v_mul_f32_e32 v34, 0xbfb8aa3b, v34
	v_exp_f32_e32 v34, v34
	v_add_f32_e32 v35, 1.0, v35
	v_rcp_f32_e32 v36, v35
	v_add_f32_e32 v35, v37, v73
	v_mul_f32_e32 v35, 0xbfb8aa3b, v35
	v_exp_f32_e32 v35, v35
	v_add_f32_e32 v34, 1.0, v34
	v_rcp_f32_e32 v34, v34
	v_add_f32_e32 v37, v41, v69
	v_add_f32_e32 v35, 1.0, v35
	v_rcp_f32_e32 v35, v35
	v_mul_f32_e32 v37, 0xbfb8aa3b, v37
	v_exp_f32_e32 v37, v37
	v_and_b32_e32 v45, 0xffff0000, v45
	v_pk_mul_f32 v[40:41], v[34:35], v[60:61]
	v_cvt_pk_bf16_f32 v38, v38, v39
	v_add_f32_e32 v34, v40, v40
	v_add_f32_e32 v35, v41, v41
	v_mul_f32_e32 v34, 0x3fb8aa3b, v34
	v_mul_f32_e32 v35, 0x3fb8aa3b, v35
	v_exp_f32_e32 v34, v34
	v_exp_f32_e32 v35, v35
	v_add_f32_e32 v37, 1.0, v37
	v_rcp_f32_e32 v37, v37
	v_sub_f32_e32 v34, 1.0, v34
	v_sub_f32_e32 v35, 1.0, v35
	v_max_f32_e32 v34, 0, v34
	v_max_f32_e32 v35, 0, v35
	v_sqrt_f32_e32 v34, v34
	v_sqrt_f32_e32 v35, v35
	s_nop 0
	v_pk_mul_f32 v[34:35], v[36:37], v[34:35]
	s_nop 0
	v_pk_mul_f32 v[36:37], v[34:35], v[44:45]
	v_cvt_pk_bf16_f32 v45, v40, v41
	v_mad_i64_i32 v[40:41], s[6:7], v42, s84, v[130:131]
	v_lshl_add_u64 v[40:41], v[40:41], 0, v[62:63]
	v_add_co_u32_e32 v40, vcc, s69, v40
	v_add_u32_e32 v34, 0x50, v42
	v_cvt_pk_bf16_f32 v44, v46, v47
	v_addc_co_u32_e32 v41, vcc, 0, v41, vcc
	v_cvt_pk_bf16_f32 v39, v36, v37
	v_mov_b32_e32 v122, v44
	v_mov_b32_e32 v123, v45
	global_store_dwordx4 v[40:41], v[120:123], off offset:2040
	v_mov_b32_e32 v126, v38
	v_mov_b32_e32 v127, v39
	global_store_dwordx4 v[40:41], v[124:127], off offset:-8
	v_pk_mul_f32 v[38:39], v[26:27], v[58:59]
	v_ashrrev_i32_e32 v35, 31, v34
	v_lshlrev_b64 v[36:37], 11, v[34:35]
	v_lshl_add_u64 v[36:37], s[14:15], 0, v[36:37]
	v_lshl_add_u64 v[36:37], v[36:37], 0, v[146:147]
	s_nop 0
	v_add_f32_e32 v26, v38, v38
	v_add_f32_e32 v27, v39, v39
	v_mul_f32_e32 v26, 0x3fb8aa3b, v26
	v_mul_f32_e32 v27, 0x3fb8aa3b, v27
	v_exp_f32_e32 v26, v26
	v_exp_f32_e32 v27, v27
	v_sub_f32_e32 v26, 1.0, v26
	v_sub_f32_e32 v27, 1.0, v27
	v_max_f32_e32 v26, 0, v26
	v_max_f32_e32 v27, 0, v27
	v_sqrt_f32_e32 v26, v26
	v_sqrt_f32_e32 v27, v27
	s_nop 0
	v_mov_b32_e32 v36, v210
	v_mov_b32_e32 v37, v211
	v_lshlrev_b32_e32 v40, 16, v36
	v_and_b32_e32 v41, 0xffff0000, v36
	v_pk_mul_f32 v[26:27], v[30:31], v[26:27]
	v_lshlrev_b32_e32 v36, 16, v37
	v_pk_mul_f32 v[30:31], v[26:27], v[40:41]
	v_add_f32_e32 v27, v32, v68
	v_mul_f32_e32 v27, 0xbfb8aa3b, v27
	v_exp_f32_e32 v27, v27
	v_add_f32_e32 v26, v28, v72
	v_mul_f32_e32 v26, 0xbfb8aa3b, v26
	v_exp_f32_e32 v26, v26
	v_add_f32_e32 v27, 1.0, v27
	v_rcp_f32_e32 v28, v27
	v_add_f32_e32 v27, v29, v73
	v_mul_f32_e32 v27, 0xbfb8aa3b, v27
	v_exp_f32_e32 v27, v27
	v_add_f32_e32 v26, 1.0, v26
	v_rcp_f32_e32 v26, v26
	v_add_f32_e32 v29, v33, v69
	v_add_f32_e32 v27, 1.0, v27
	v_rcp_f32_e32 v27, v27
	v_mul_f32_e32 v29, 0xbfb8aa3b, v29
	v_exp_f32_e32 v29, v29
	v_and_b32_e32 v37, 0xffff0000, v37
	v_pk_mul_f32 v[32:33], v[26:27], v[60:61]
	v_cvt_pk_bf16_f32 v30, v30, v31
	v_add_f32_e32 v26, v32, v32
	v_add_f32_e32 v27, v33, v33
	v_mul_f32_e32 v26, 0x3fb8aa3b, v26
	v_mul_f32_e32 v27, 0x3fb8aa3b, v27
	v_exp_f32_e32 v26, v26
	v_exp_f32_e32 v27, v27
	v_add_f32_e32 v29, 1.0, v29
	v_rcp_f32_e32 v29, v29
	v_sub_f32_e32 v26, 1.0, v26
	v_sub_f32_e32 v27, 1.0, v27
	v_max_f32_e32 v26, 0, v26
	v_max_f32_e32 v27, 0, v27
	v_sqrt_f32_e32 v26, v26
	v_sqrt_f32_e32 v27, v27
	s_nop 0
	v_pk_mul_f32 v[26:27], v[28:29], v[26:27]
	s_nop 0
	v_pk_mul_f32 v[28:29], v[26:27], v[36:37]
	v_cvt_pk_bf16_f32 v37, v32, v33
	v_mad_i64_i32 v[32:33], s[6:7], v34, s84, v[130:131]
	v_lshl_add_u64 v[32:33], v[32:33], 0, v[62:63]
	v_add_co_u32_e32 v32, vcc, s69, v32
	v_add_u32_e32 v26, 16, v34
	v_cvt_pk_bf16_f32 v36, v38, v39
	v_addc_co_u32_e32 v33, vcc, 0, v33, vcc
	v_cvt_pk_bf16_f32 v31, v28, v29
	v_mov_b32_e32 v114, v36
	v_mov_b32_e32 v115, v37
	global_store_dwordx4 v[32:33], v[112:115], off offset:2040
	v_mov_b32_e32 v118, v30
	v_mov_b32_e32 v119, v31
	global_store_dwordx4 v[32:33], v[116:119], off offset:-8
	v_pk_mul_f32 v[30:31], v[18:19], v[58:59]
	v_ashrrev_i32_e32 v27, 31, v26
	v_lshlrev_b64 v[28:29], 11, v[26:27]
	v_lshl_add_u64 v[28:29], s[14:15], 0, v[28:29]
	v_lshl_add_u64 v[28:29], v[28:29], 0, v[146:147]
	s_nop 0
	v_add_f32_e32 v18, v30, v30
	v_add_f32_e32 v19, v31, v31
	v_mul_f32_e32 v18, 0x3fb8aa3b, v18
	v_mul_f32_e32 v19, 0x3fb8aa3b, v19
	v_exp_f32_e32 v18, v18
	v_exp_f32_e32 v19, v19
	v_sub_f32_e32 v18, 1.0, v18
	v_sub_f32_e32 v19, 1.0, v19
	v_max_f32_e32 v18, 0, v18
	v_max_f32_e32 v19, 0, v19
	v_sqrt_f32_e32 v18, v18
	v_sqrt_f32_e32 v19, v19
	s_nop 0
	v_mov_b32_e32 v28, v212
	v_mov_b32_e32 v29, v213
	v_lshlrev_b32_e32 v32, 16, v28
	v_and_b32_e32 v33, 0xffff0000, v28
	v_pk_mul_f32 v[18:19], v[22:23], v[18:19]
	v_lshlrev_b32_e32 v28, 16, v29
	v_pk_mul_f32 v[22:23], v[18:19], v[32:33]
	v_add_f32_e32 v19, v24, v68
	v_mul_f32_e32 v19, 0xbfb8aa3b, v19
	v_exp_f32_e32 v19, v19
	v_add_f32_e32 v18, v20, v72
	v_mul_f32_e32 v18, 0xbfb8aa3b, v18
	v_exp_f32_e32 v18, v18
	v_add_f32_e32 v19, 1.0, v19
	v_rcp_f32_e32 v20, v19
	v_add_f32_e32 v19, v21, v73
	v_mul_f32_e32 v19, 0xbfb8aa3b, v19
	v_exp_f32_e32 v19, v19
	v_add_f32_e32 v18, 1.0, v18
	v_rcp_f32_e32 v18, v18
	v_add_f32_e32 v21, v25, v69
	v_add_f32_e32 v19, 1.0, v19
	v_rcp_f32_e32 v19, v19
	v_mul_f32_e32 v21, 0xbfb8aa3b, v21
	v_exp_f32_e32 v21, v21
	v_and_b32_e32 v29, 0xffff0000, v29
	v_pk_mul_f32 v[24:25], v[18:19], v[60:61]
	v_cvt_pk_bf16_f32 v22, v22, v23
	v_add_f32_e32 v18, v24, v24
	v_add_f32_e32 v19, v25, v25
	v_mul_f32_e32 v18, 0x3fb8aa3b, v18
	v_mul_f32_e32 v19, 0x3fb8aa3b, v19
	v_exp_f32_e32 v18, v18
	v_exp_f32_e32 v19, v19
	v_add_f32_e32 v21, 1.0, v21
	v_rcp_f32_e32 v21, v21
	v_sub_f32_e32 v18, 1.0, v18
	v_sub_f32_e32 v19, 1.0, v19
	v_max_f32_e32 v18, 0, v18
	v_max_f32_e32 v19, 0, v19
	v_sqrt_f32_e32 v18, v18
	v_sqrt_f32_e32 v19, v19
	s_nop 0
	v_pk_mul_f32 v[18:19], v[20:21], v[18:19]
	s_nop 0
	v_pk_mul_f32 v[20:21], v[18:19], v[28:29]
	v_cvt_pk_bf16_f32 v29, v24, v25
	v_mad_i64_i32 v[24:25], s[6:7], v26, s84, v[130:131]
	v_lshl_add_u64 v[24:25], v[24:25], 0, v[62:63]
	v_add_co_u32_e32 v24, vcc, s69, v24
	v_add_u32_e32 v18, 16, v26
	v_cvt_pk_bf16_f32 v28, v30, v31
	v_addc_co_u32_e32 v25, vcc, 0, v25, vcc
	v_cvt_pk_bf16_f32 v23, v20, v21
	v_mov_b32_e32 v106, v28
	v_mov_b32_e32 v107, v29
	global_store_dwordx4 v[24:25], v[104:107], off offset:2040
	v_mov_b32_e32 v110, v22
	v_mov_b32_e32 v111, v23
	global_store_dwordx4 v[24:25], v[108:111], off offset:-8
	v_pk_mul_f32 v[22:23], v[10:11], v[58:59]
	v_ashrrev_i32_e32 v19, 31, v18
	v_lshlrev_b64 v[20:21], 11, v[18:19]
	v_lshl_add_u64 v[20:21], s[14:15], 0, v[20:21]
	v_lshl_add_u64 v[20:21], v[20:21], 0, v[146:147]
	s_nop 0
	v_add_f32_e32 v10, v22, v22
	v_add_f32_e32 v11, v23, v23
	v_mul_f32_e32 v10, 0x3fb8aa3b, v10
	v_mul_f32_e32 v11, 0x3fb8aa3b, v11
	v_exp_f32_e32 v10, v10
	v_exp_f32_e32 v11, v11
	v_sub_f32_e32 v10, 1.0, v10
	v_sub_f32_e32 v11, 1.0, v11
	v_max_f32_e32 v10, 0, v10
	v_max_f32_e32 v11, 0, v11
	v_sqrt_f32_e32 v10, v10
	v_sqrt_f32_e32 v11, v11
	s_nop 0
	v_mov_b32_e32 v20, v214
	v_mov_b32_e32 v21, v215
	v_lshlrev_b32_e32 v24, 16, v20
	v_and_b32_e32 v25, 0xffff0000, v20
	v_pk_mul_f32 v[10:11], v[14:15], v[10:11]
	v_lshlrev_b32_e32 v20, 16, v21
	v_pk_mul_f32 v[14:15], v[10:11], v[24:25]
	v_add_f32_e32 v11, v16, v68
	v_mul_f32_e32 v11, 0xbfb8aa3b, v11
	v_exp_f32_e32 v11, v11
	v_add_f32_e32 v10, v12, v72
	v_mul_f32_e32 v10, 0xbfb8aa3b, v10
	v_exp_f32_e32 v10, v10
	v_add_f32_e32 v11, 1.0, v11
	v_rcp_f32_e32 v12, v11
	v_add_f32_e32 v11, v13, v73
	v_mul_f32_e32 v11, 0xbfb8aa3b, v11
	v_exp_f32_e32 v11, v11
	v_add_f32_e32 v10, 1.0, v10
	v_rcp_f32_e32 v10, v10
	v_add_f32_e32 v13, v17, v69
	v_add_f32_e32 v11, 1.0, v11
	v_rcp_f32_e32 v11, v11
	v_mul_f32_e32 v13, 0xbfb8aa3b, v13
	v_exp_f32_e32 v13, v13
	v_and_b32_e32 v21, 0xffff0000, v21
	v_pk_mul_f32 v[16:17], v[10:11], v[60:61]
	v_cvt_pk_bf16_f32 v14, v14, v15
	v_add_f32_e32 v10, v16, v16
	v_add_f32_e32 v11, v17, v17
	v_mul_f32_e32 v10, 0x3fb8aa3b, v10
	v_mul_f32_e32 v11, 0x3fb8aa3b, v11
	v_exp_f32_e32 v10, v10
	v_exp_f32_e32 v11, v11
	v_add_f32_e32 v13, 1.0, v13
	v_rcp_f32_e32 v13, v13
	v_sub_f32_e32 v10, 1.0, v10
	v_sub_f32_e32 v11, 1.0, v11
	v_max_f32_e32 v10, 0, v10
	v_max_f32_e32 v11, 0, v11
	v_sqrt_f32_e32 v10, v10
	v_sqrt_f32_e32 v11, v11
	s_nop 0
	v_pk_mul_f32 v[10:11], v[12:13], v[10:11]
	s_nop 0
	v_pk_mul_f32 v[12:13], v[10:11], v[20:21]
	v_cvt_pk_bf16_f32 v21, v16, v17
	v_mad_i64_i32 v[16:17], s[6:7], v18, s84, v[130:131]
	v_lshl_add_u64 v[16:17], v[16:17], 0, v[62:63]
	v_add_co_u32_e32 v16, vcc, s69, v16
	v_add_u32_e32 v10, 16, v18
	v_cvt_pk_bf16_f32 v20, v22, v23
	v_addc_co_u32_e32 v17, vcc, 0, v17, vcc
	v_cvt_pk_bf16_f32 v15, v12, v13
	v_mov_b32_e32 v98, v20
	v_mov_b32_e32 v99, v21
	global_store_dwordx4 v[16:17], v[96:99], off offset:2040
	v_mov_b32_e32 v102, v14
	v_mov_b32_e32 v103, v15
	global_store_dwordx4 v[16:17], v[100:103], off offset:-8
	s_nop 0
	v_ashrrev_i32_e32 v11, 31, v10
	v_lshlrev_b64 v[12:13], 11, v[10:11]
	v_lshl_add_u64 v[12:13], s[14:15], 0, v[12:13]
	v_lshl_add_u64 v[12:13], v[12:13], 0, v[146:147]
	s_nop 0
	v_add_f32_e32 v11, v2, v2
	v_mul_f32_e32 v11, 0x3fb8aa3b, v11
	v_exp_f32_e32 v11, v11
	v_cvt_pk_bf16_f32 v2, v2, v3
	v_sub_f32_e32 v11, 1.0, v11
	v_max_f32_e32 v11, 0, v11
	v_sqrt_f32_e32 v14, v11
	v_add_f32_e32 v11, v3, v3
	v_mul_f32_e32 v11, 0x3fb8aa3b, v11
	v_exp_f32_e32 v11, v11
	v_cvt_pk_bf16_f32 v3, v4, v5
	v_sub_f32_e32 v11, 1.0, v11
	v_max_f32_e32 v11, 0, v11
	v_sqrt_f32_e32 v15, v11
	v_add_f32_e32 v11, v4, v4
	v_mul_f32_e32 v11, 0x3fb8aa3b, v11
	v_exp_f32_e32 v11, v11
	v_pk_mul_f32 v[6:7], v[6:7], v[14:15]
	v_sub_f32_e32 v11, 1.0, v11
	v_max_f32_e32 v11, 0, v11
	v_sqrt_f32_e32 v14, v11
	v_add_f32_e32 v11, v5, v5
	v_mul_f32_e32 v11, 0x3fb8aa3b, v11
	v_exp_f32_e32 v11, v11
	v_mad_i64_i32 v[4:5], s[6:7], v10, s84, v[130:131]
	v_lshl_add_u64 v[4:5], v[4:5], 0, v[62:63]
	v_sub_f32_e32 v11, 1.0, v11
	v_max_f32_e32 v11, 0, v11
	v_sqrt_f32_e32 v15, v11
	v_add_co_u32_e32 v4, vcc, s69, v4
	v_pk_mul_f32 v[8:9], v[8:9], v[14:15]
	s_nop 0
	v_addc_co_u32_e32 v5, vcc, 0, v5, vcc
	v_mov_b32_e32 v90, v2
	v_mov_b32_e32 v91, v3
	global_store_dwordx4 v[4:5], v[88:91], off offset:2040
	s_andn2_b64 vcc, exec, s[4:5]
	s_nop 0
	v_mov_b32_e32 v12, v216
	v_mov_b32_e32 v13, v217
	v_lshlrev_b32_e32 v16, 16, v12
	v_and_b32_e32 v17, 0xffff0000, v12
	v_lshlrev_b32_e32 v12, 16, v13
	v_and_b32_e32 v13, 0xffff0000, v13
	v_pk_mul_f32 v[6:7], v[6:7], v[16:17]
	v_pk_mul_f32 v[8:9], v[8:9], v[12:13]
	v_cvt_pk_bf16_f32 v2, v6, v7
	v_cvt_pk_bf16_f32 v3, v8, v9
	v_mov_b32_e32 v94, v2
	v_mov_b32_e32 v95, v3
	global_store_dwordx4 v[4:5], v[92:95], off offset:-8
	s_cbranch_vccz .LBB0_1214
